# plus GEMM-epilogue stores and residual/gate loads issued as global_* instead of flat_* (no lgkmcnt coupling)
# speedup vs baseline: 1.0010x; 1.0010x over previous
; __device__ __forceinline__ float rope_inv32(int i) { return exp2f(-(float)(2 * i) * (L2THETA / 16.0f)); }
; __global__ void __launch_bounds__(512, 2) fwd_mega(Args args) {
;     ...
;                 const int sub = lane & 15;
;                 float gs0[8], gs1[8], gs2[8], ik8[8];
;                 { const float* gqn = ap->in[20] + l * 64; const float* gkn = ap->in[21] + l * 64; const float* gqr = ap->in[22] + l * 32;
; #pragma unroll
;                   for (int e = 0; e < 8; ++e) {
;                       const float gq = sub < 8 ? gqn[8 * sub + e] * QSCALE_M : (sub < 12 ? gqr[8 * (sub - 8) + e] * QSCALE_M : 0.f);
;                       const float gk = sub < 8 ? gkn[8 * sub + e] : 0.f;
;                       gs0[e] = gq; gs1[e] = lane < 32 ? gq : gk; gs2[e] = gk; ik8[e] = rope_inv32(e); } }
.LBB0_24:
	s_mov_b64 s[22:23], 0
	s_mov_b64 s[38:39], 0
	s_cbranch_execz .LBB0_93
	v_mov_b64_e32 v[6:7], s[0:1]
	global_load_dwordx4 v[2:5], v[6:7], off offset:160
	s_nop 0
	flat_load_dwordx2 v[6:7], v[6:7] offset:176
	s_lshl_b32 s4, s26, 5
	v_and_b32_e32 v10, 15, v198
	s_ashr_i32 s5, s4, 31
	v_cmp_gt_u32_e64 s[42:43], 8, v10
	v_cmp_lt_u32_e64 s[40:41], 7, v10
	v_cmp_gt_u32_e64 s[44:45], 12, v10
	v_lshlrev_b32_e32 v11, 3, v10
	s_waitcnt vmcnt(0) lgkmcnt(0)
	v_lshl_add_u64 v[6:7], s[4:5], 2, v[6:7]
	s_and_saveexec_b64 s[4:5], s[40:41]
	s_xor_b64 s[46:47], exec, s[4:5]
	s_cbranch_execz .LBB0_29
	v_mov_b32_e32 v36, 0
	s_and_saveexec_b64 s[48:49], s[44:45]
	s_cbranch_execz .LBB0_28
	v_lshlrev_b32_e32 v0, 2, v11
	v_lshl_add_u64 v[8:9], v[6:7], 0, v[0:1]
	v_add_co_u32_e32 v8, vcc, 0xffffff00, v8
	s_nop 1
	v_addc_co_u32_e32 v9, vcc, -1, v9, vcc
	flat_load_dword v0, v[8:9]
	s_waitcnt vmcnt(0) lgkmcnt(0)
	v_mul_f32_e32 v36, 0x3e16c740, v0

; #define GAS __attribute__((address_space(1)))
; __device__ __forceinline__ float rope_inv64(int i) { return exp2f(-(float)(2 * i) * (L2THETA / 32.0f)); }
; __device__ __forceinline__ float rope_inv32(int i) { return exp2f(-(float)(2 * i) * (L2THETA / 16.0f)); }
; __global__ void __launch_bounds__(512, 2) fwd_mega(Args args) {
;     ...
;             } else if ((EN & 32) && sp == 5) {
;                 const GAS bf16* P = (const GAS bf16*)(ws + WS_P);
;                 GAS bf16* CQKV = (GAS bf16*)(ws + WS_CQKV); GAS bf16* QA = (GAS bf16*)(ws + WS_QA); GAS bf16* KA = (GAS bf16*)(ws + WS_KA);
;                 GAS bf16* VA = (GAS bf16*)(ws + WS_VA); GAS bf16* KM = (GAS bf16*)(ws + WS_KM); GAS bf16* YC = (GAS bf16*)(ws + WS_YC);
;                 const int hh = lane >> 3, dim0 = (lane & 7) * 8;
;                 float g8[8], inv8[8], ik8[8], gkr8[8], gc0[8], gc1[8], cw0[4], cw1[4], cw2[4], cb4[4];
;                 { const float* gsrc = (hh < 6 ? ap->in[12] : ap->in[13]) + l * 64 + dim0;
;                   const float* gcq = ap->in[16] + l * 384; const float* gckv = ap->in[17] + l * 256; const float* gkr = ap->in[23] + l * 32 + (lane & 3) * 8;
;                   const float* cw = ap->in[14] + l * 3 * 256 + 4 * lane; const float* cb = ap->in[15] + l * 256 + 4 * lane;
; #pragma unroll
;                   for (int e = 0; e < 8; ++e) { g8[e] = gsrc[e] * (hh < 6 ? QSCALE_A : 1.0f); inv8[e] = rope_inv64((lane & 1) * 8 + e); ik8[e] = rope_inv32(e); gkr8[e] = gkr[e];
;                       gc0[e] = lane < 48 ? gcq[8 * lane + e] : gckv[8 * (lane - 48) + e]; gc1[e] = gckv[128 + 8 * (lane & 15) + e]; }
; #pragma unroll
;                   for (int i = 0; i < 4; ++i) { cw0[i] = cw[i]; cw1[i] = cw[256 + i]; cw2[i] = cw[512 + i]; cb4[i] = cb[i]; } }
.LBB0_94:
	s_cmp_gt_i32 s84, 2
	s_mov_b64 s[56:57], -1
	s_cbranch_scc0 .LBB0_381
	s_cmp_gt_i32 s84, 4
	s_mov_b64 s[40:41], -1
	s_cbranch_scc0 .LBB0_378
	s_cmp_eq_u32 s84, 5
	s_mov_b64 s[22:23], -1
	s_cbranch_scc0 .LBB0_377
	v_ashrrev_i32_e32 v38, 3, v198
	v_cmp_gt_i32_e32 vcc, 6, v38
	v_mov_b64_e32 v[2:3], s[0:1]
	global_load_dwordx4 v[6:9], v[2:3], off offset:128
	flat_load_dwordx2 v[10:11], v[2:3] offset:184
	v_cndmask_b32_e32 v0, v231, v249, vcc
	v_lshl_add_u64 v[4:5], s[0:1], 0, v[0:1]
	flat_load_dwordx2 v[12:13], v[4:5]
	s_mul_i32 s6, s26, 0x180
	s_lshl_b32 s22, s26, 8
	s_waitcnt vmcnt(0) lgkmcnt(0)
	v_lshlrev_b32_e32 v18, 3, v198
	s_lshl_b32 s4, s26, 6
	s_lshl_b32 s8, s26, 5
	s_ashr_i32 s7, s6, 31
	s_ashr_i32 s23, s22, 31
	v_add_u32_e32 v4, 0xfffffe80, v18
	v_cmp_gt_i32_e64 s[40:41], 48, v198
	v_and_b32_e32 v27, 7, v198
	s_ashr_i32 s5, s4, 31
	s_ashr_i32 s9, s8, 31
	v_cndmask_b32_e64 v14, v4, v18, s[40:41]
	v_and_b32_e32 v26, 3, v198
	v_lshlrev_b32_e32 v0, 5, v27
	v_ashrrev_i32_e32 v15, 31, v14
	v_lshlrev_b32_e32 v19, 5, v198
	global_load_dwordx4 v[2:5], v[2:3], off offset:112
	v_cmp_lt_i32_e64 s[42:43], 5, v38
	v_cmp_lt_i32_e64 s[44:45], 47, v198
	v_lshl_add_u64 v[6:7], s[6:7], 2, v[6:7]
	v_lshl_add_u64 v[8:9], s[22:23], 2, v[8:9]
	v_lshl_add_u64 v[16:17], s[8:9], 2, v[10:11]
	v_cndmask_b32_e64 v11, v9, v7, s[40:41]
	v_cndmask_b32_e64 v10, v8, v6, s[40:41]
	v_lshl_add_u64 v[12:13], s[4:5], 2, v[12:13]
	v_lshl_add_u64 v[14:15], v[14:15], 2, v[10:11]
	v_lshl_add_u64 v[10:11], v[12:13], 0, v[0:1]
	v_lshlrev_b32_e32 v0, 5, v26
	v_lshl_add_u64 v[12:13], v[16:17], 0, v[0:1]
	v_and_b32_e32 v0, 0x1e0, v19
	v_lshl_add_u64 v[22:23], v[8:9], 0, v[0:1]
	flat_load_dword v40, v[14:15]
	flat_load_dwordx2 v[20:21], v[10:11]
	flat_load_dword v42, v[22:23] offset:512
	flat_load_dwordx2 v[44:45], v[12:13]
	s_and_saveexec_b64 s[4:5], s[44:45]
	s_xor_b64 s[46:47], exec, s[4:5]
	v_add_u32_e32 v14, 0xfffffe81, v18
	v_ashrrev_i32_e32 v15, 31, v14
	v_lshl_add_u64 v[14:15], v[14:15], 2, v[8:9]
	s_or_saveexec_b64 s[46:47], s[46:47]
	v_ashrrev_i32_e32 v19, 31, v18
	s_xor_b64 exec, exec, s[46:47]
	v_lshl_add_u64 v[14:15], v[18:19], 2, v[6:7]
	v_lshl_add_u64 v[14:15], v[14:15], 0, 4
	s_or_b64 exec, exec, s[46:47]
	flat_load_dword v41, v[14:15]
	flat_load_dword v43, v[22:23] offset:516
	flat_load_dword v28, v[10:11] offset:8
	flat_load_dword v46, v[12:13] offset:8
	s_and_saveexec_b64 s[4:5], s[44:45]
	s_xor_b64 s[46:47], exec, s[4:5]
	v_add_u32_e32 v14, 0xfffffe82, v18
	v_ashrrev_i32_e32 v15, 31, v14
	v_lshl_add_u64 v[14:15], v[14:15], 2, v[8:9]
	s_andn2_saveexec_b64 s[46:47], s[46:47]
	v_lshl_add_u64 v[14:15], v[18:19], 2, v[6:7]
	v_lshl_add_u64 v[14:15], v[14:15], 0, 8
	s_or_b64 exec, exec, s[46:47]
	flat_load_dword v48, v[14:15]
	flat_load_dword v50, v[22:23] offset:520
	flat_load_dword v29, v[10:11] offset:12
	flat_load_dword v47, v[12:13] offset:12
	s_and_saveexec_b64 s[4:5], s[44:45]
	s_xor_b64 s[46:47], exec, s[4:5]
	v_add_u32_e32 v14, 0xfffffe83, v18
	v_ashrrev_i32_e32 v15, 31, v14
	v_lshl_add_u64 v[14:15], v[14:15], 2, v[8:9]
	s_andn2_saveexec_b64 s[46:47], s[46:47]
	v_lshl_add_u64 v[14:15], v[18:19], 2, v[6:7]
	v_lshl_add_u64 v[14:15], v[14:15], 0, 12
	s_or_b64 exec, exec, s[46:47]
	flat_load_dword v49, v[14:15]
	flat_load_dword v51, v[22:23] offset:524
	flat_load_dword v30, v[10:11] offset:16
	flat_load_dword v52, v[12:13] offset:16
	s_and_saveexec_b64 s[4:5], s[44:45]
	s_xor_b64 s[46:47], exec, s[4:5]
	v_add_u32_e32 v14, 0xfffffe84, v18
	v_ashrrev_i32_e32 v15, 31, v14
	v_lshl_add_u64 v[14:15], v[14:15], 2, v[8:9]
	s_andn2_saveexec_b64 s[46:47], s[46:47]
	v_lshl_add_u64 v[14:15], v[18:19], 2, v[6:7]
	v_lshl_add_u64 v[14:15], v[14:15], 0, 16
	s_or_b64 exec, exec, s[46:47]
	flat_load_dword v54, v[14:15]
	flat_load_dword v56, v[22:23] offset:528
	flat_load_dword v31, v[10:11] offset:20
	flat_load_dword v53, v[12:13] offset:20
	s_and_saveexec_b64 s[4:5], s[44:45]
	s_xor_b64 s[46:47], exec, s[4:5]
	v_add_u32_e32 v14, 0xfffffe85, v18
	v_ashrrev_i32_e32 v15, 31, v14
	v_lshl_add_u64 v[14:15], v[14:15], 2, v[8:9]
	s_andn2_saveexec_b64 s[46:47], s[46:47]
	v_lshl_add_u64 v[14:15], v[18:19], 2, v[6:7]
	v_lshl_add_u64 v[14:15], v[14:15], 0, 20
	s_or_b64 exec, exec, s[46:47]
	flat_load_dword v55, v[14:15]
	flat_load_dword v57, v[22:23] offset:532
	flat_load_dword v32, v[10:11] offset:24
	flat_load_dword v58, v[12:13] offset:24
	s_and_saveexec_b64 s[4:5], s[44:45]
	s_xor_b64 s[46:47], exec, s[4:5]
	v_add_u32_e32 v14, 0xfffffe86, v18
	v_ashrrev_i32_e32 v15, 31, v14
	v_lshl_add_u64 v[14:15], v[14:15], 2, v[8:9]
	s_andn2_saveexec_b64 s[46:47], s[46:47]
	v_lshl_add_u64 v[14:15], v[18:19], 2, v[6:7]
	v_lshl_add_u64 v[14:15], v[14:15], 0, 24
	s_or_b64 exec, exec, s[46:47]
	flat_load_dword v60, v[14:15]
	flat_load_dword v62, v[22:23] offset:536
	flat_load_dword v33, v[10:11] offset:28
	flat_load_dword v59, v[12:13] offset:28
	s_and_saveexec_b64 s[4:5], s[44:45]
	s_xor_b64 s[44:45], exec, s[4:5]
	s_cbranch_execz .LBB0_185
	v_add_u32_e32 v6, 0xfffffe87, v18
	v_ashrrev_i32_e32 v7, 31, v6
	v_lshl_add_u64 v[24:25], v[6:7], 2, v[8:9]
	s_andn2_saveexec_b64 s[44:45], s[44:45]
	s_cbranch_execnz .LBB0_186

; __global__ void __launch_bounds__(512, 2) fwd_mega(Args args) {
;     ...
;                 { const float* gsrc = (hh < 6 ? ap->in[12] : ap->in[13]) + l * 64 + dim0;
;                   const float* gcq = ap->in[16] + l * 384; const float* gckv = ap->in[17] + l * 256; const float* gkr = ap->in[23] + l * 32 + (lane & 3) * 8;
;                   const float* cw = ap->in[14] + l * 3 * 256 + 4 * lane; const float* cb = ap->in[15] + l * 256 + 4 * lane;
; #pragma unroll
;                   for (int e = 0; e < 8; ++e) { g8[e] = gsrc[e] * (hh < 6 ? QSCALE_A : 1.0f); inv8[e] = rope_inv64((lane & 1) * 8 + e); ik8[e] = rope_inv32(e); gkr8[e] = gkr[e];
;                       gc0[e] = lane < 48 ? gcq[8 * lane + e] : gckv[8 * (lane - 48) + e]; gc1[e] = gckv[128 + 8 * (lane & 15) + e]; }
; #pragma unroll
;                   for (int i = 0; i < 4; ++i) { cw0[i] = cw[i]; cw1[i] = cw[256 + i]; cw2[i] = cw[512 + i]; cb4[i] = cb[i]; } }
;     ...
;                 for (int r = gw; r < MTOT; r += NGW) {
;                     const bool lat = r < MLAT; int b, s;
;                     if (lat) { b = r >> 11; s = r & 2047; } else { b = (r - MLAT) >> 8; s = (r - MLAT) & 255; }
;                     const int pos = lat ? CTXL + s : s, smax = lat ? SEQ - 1 : CTXL - 1;
;                     const float prow = (float)(s >> 6), pcol = (float)(s & 63);
;                     const GAS bf16* p = P + (size_t)r * INP;
;                     const u32x4 a8 = *(const GAS u32x4*)(p + 8 * lane);
;                     const u32x4 v8 = *(const GAS u32x4*)(p + PC_V + 8 * (lane & 15));
;                     const u32x4 c0 = *(const GAS u32x4*)(p + PC_CQ + 8 * lane);
;                     const u32x4 c1 = *(const GAS u32x4*)(p + PC_CQ + 512 + 8 * (lane & 15));
;                     const u32x4 k8 = *(const GAS u32x4*)(p + PC_KR + 8 * (lane & 3));
;                     const u32x2 xi = *(const GAS u32x2*)(p + PC_X + 4 * lane), cg = *(const GAS u32x2*)(p + PC_CG + 4 * lane), bg = *(const GAS u32x2*)(p + PC_BG + 4 * lane);
;                     u32x2 xm = (u32x2){0u, 0u}, cm = xm, xp = xm, cp = xm;
;                     if (s > 0) { xm = *(const GAS u32x2*)(p - INP + PC_X + 4 * lane); cm = *(const GAS u32x2*)(p - INP + PC_CG + 4 * lane); }
;                     if (s < smax) { xp = *(const GAS u32x2*)(p + INP + PC_X + 4 * lane); cp = *(const GAS u32x2*)(p + INP + PC_CG + 4 * lane); }
.LBB0_187:
	v_lshlrev_b32_e32 v0, 3, v27
	s_mul_i32 s4, s26, 0x300
	s_ashr_i32 s5, s4, 31
	v_lshlrev_b32_e32 v0, 1, v0
	s_waitcnt vmcnt(0) lgkmcnt(0)
	v_lshl_add_u64 v[2:3], s[4:5], 2, v[2:3]
	v_lshl_add_u64 v[36:37], s[34:35], 0, v[0:1]
	s_mov_b64 s[4:5], 0x18d00000
	v_lshl_add_u64 v[64:65], v[36:37], 0, s[4:5]
	v_lshlrev_b32_e32 v36, 1, v18
	v_and_b32_e32 v37, 16, v36
	v_or_b32_e32 v36, 14, v37
	v_cvt_f32_ubyte0_e32 v36, v36
	v_mul_f32_e32 v39, 0xbed49a78, v36
	s_mov_b32 s4, 0xc2fc0000
	v_cmp_gt_f32_e64 s[44:45], s4, v39
	v_or_b32_e32 v61, 10, v37
	v_cvt_f32_ubyte0_e32 v61, v61
	v_cndmask_b32_e64 v39, 0, v225, s[44:45]
	v_fmac_f32_e32 v39, 0xbed49a78, v36
	v_exp_f32_e32 v39, v39
	v_cndmask_b32_e32 v36, 1.0, v224, vcc
	v_mul_f32_e32 v66, v36, v32
	v_or_b32_e32 v32, 12, v37
	v_mul_f32_e32 v67, v36, v33
	v_cndmask_b32_e64 v33, 0, v247, s[44:45]
	v_cvt_f32_ubyte0_e32 v32, v32
	v_ldexp_f32 v39, v39, v33
	v_mul_f32_e32 v33, 0xbed49a78, v32
	v_cmp_gt_f32_e32 vcc, s4, v33
	v_mul_f32_e32 v63, 0xbed49a78, v61
	v_lshlrev_b32_e32 v34, 2, v198
	v_cndmask_b32_e32 v33, 0, v225, vcc
	v_fmac_f32_e32 v33, 0xbed49a78, v32
	v_exp_f32_e32 v32, v33
	v_cndmask_b32_e32 v33, 0, v247, vcc
	v_cmp_gt_f32_e32 vcc, s4, v63
	v_ashrrev_i32_e32 v35, 31, v34
	v_lshl_add_u64 v[4:5], s[22:23], 2, v[4:5]
	v_cndmask_b32_e32 v63, 0, v225, vcc
	v_fmac_f32_e32 v63, 0xbed49a78, v61
	v_lshlrev_b64 v[6:7], 2, v[34:35]
	v_exp_f32_e32 v61, v63
	v_lshl_add_u64 v[10:11], v[2:3], 0, v[6:7]
	v_lshl_add_u64 v[14:15], v[4:5], 0, v[6:7]
	global_load_dwordx4 v[2:5], v[10:11], off
	global_load_dwordx4 v[6:9], v[10:11], off offset:1024
	s_nop 0
	global_load_dwordx4 v[10:13], v[10:11], off offset:2048
	s_nop 0
	global_load_dwordx4 v[14:17], v[14:15], off
	v_mul_f32_e32 v69, v36, v31
	v_cndmask_b32_e32 v31, 0, v247, vcc
	v_ldexp_f32 v112, v61, v31
	flat_load_dword v63, v[22:23] offset:540
	flat_load_dword v61, v[24:25]
	v_mul_f32_e32 v68, v36, v30
	v_or_b32_e32 v30, 8, v37
	v_cvt_f32_ubyte0_e32 v30, v30
	v_mul_f32_e32 v31, 0xbed49a78, v30
	v_ldexp_f32 v75, v32, v33
	v_cmp_gt_f32_e32 vcc, s4, v31
	v_or_b32_e32 v32, 6, v37
	v_cvt_f32_ubyte0_e32 v32, v32
	v_cndmask_b32_e32 v31, 0, v225, vcc
	v_fmac_f32_e32 v31, 0xbed49a78, v30
	v_mul_f32_e32 v33, 0xbed49a78, v32
	v_exp_f32_e32 v30, v31
	v_cndmask_b32_e32 v31, 0, v247, vcc
	v_cmp_gt_f32_e32 vcc, s4, v33
	v_mul_f32_e32 v71, v36, v29
	v_ldexp_f32 v113, v30, v31
	v_cndmask_b32_e32 v33, 0, v225, vcc
	v_fmac_f32_e32 v33, 0xbed49a78, v32
	v_exp_f32_e32 v32, v33
	v_cndmask_b32_e32 v29, 0, v247, vcc
	v_or_b32_e32 v24, 2, v37
	v_cvt_f32_ubyte0_e32 v24, v24
	v_ldexp_f32 v114, v32, v29
	v_or_b32_e32 v29, 4, v37
	v_cvt_f32_ubyte0_e32 v29, v29
	v_mul_f32_e32 v30, 0xbed49a78, v29
	v_cmp_gt_f32_e32 vcc, s4, v30
	v_mul_f32_e32 v25, 0xbed49a78, v24
	v_pk_mul_f32 v[72:73], v[36:37], v[20:21] op_sel_hi:[0,1]
	v_cndmask_b32_e32 v30, 0, v225, vcc
	v_fmac_f32_e32 v30, 0xbed49a78, v29
	v_exp_f32_e32 v29, v30
	v_cndmask_b32_e32 v22, 0, v247, vcc
	s_add_u32 s22, s34, 0x17b00000
	v_lshlrev_b32_e32 v76, 3, v26
	v_ldexp_f32 v115, v29, v22
	v_cvt_f32_ubyte0_e32 v22, v37
	v_mul_f32_e32 v23, 0xbed49a78, v22
	v_cmp_gt_f32_e32 vcc, s4, v23
	s_addc_u32 s23, s35, 0
	s_add_u32 s60, s34, 0x18880000
	v_cndmask_b32_e32 v23, 0, v225, vcc
	v_fmac_f32_e32 v23, 0xbed49a78, v22
	v_exp_f32_e32 v22, v23
	v_cndmask_b32_e32 v23, 0, v247, vcc
	v_cmp_gt_f32_e32 vcc, s4, v25
	v_mov_b32_e32 v21, v1
	s_addc_u32 s61, s35, 0
	v_cndmask_b32_e32 v25, 0, v225, vcc
	v_fmac_f32_e32 v25, 0xbed49a78, v24
	v_exp_f32_e32 v24, v25
	v_cndmask_b32_e32 v20, 0, v247, vcc
	s_mov_b64 s[4:5], 0x1a5c0000
	s_mov_b32 s6, s21
	v_ldexp_f32 v117, v24, v20
	v_and_b32_e32 v20, 2, v198
	v_cmp_eq_u32_e64 s[46:47], 0, v20
	v_and_b32_e32 v20, 1, v198
	v_cmp_eq_u32_e64 s[52:53], 0, v20
	v_lshlrev_b32_e32 v20, 1, v76
	v_lshl_add_u64 v[20:21], s[34:35], 0, v[20:21]
	s_ashr_i32 s21, s20, 31
	v_lshl_add_u64 v[76:77], v[20:21], 0, s[4:5]
	s_lshl_b64 s[4:5], s[20:21], 11
	s_add_u32 s4, s34, s4
	v_lshlrev_b64 v[78:79], 1, v[34:35]
	s_addc_u32 s5, s35, s5
	v_lshl_add_u64 v[20:21], s[4:5], 0, v[78:79]
	s_mov_b64 s[4:5], 0x1c780300
	v_lshl_add_u64 v[80:81], v[20:21], 0, s[4:5]
	s_ashr_i32 s37, s36, 31
	v_lshlrev_b64 v[18:19], 1, v[18:19]
	s_mov_b64 s[4:5], 0xb00
	s_lshl_b64 s[70:71], s[36:37], 11
	v_lshl_add_u64 v[82:83], v[18:19], 0, s[4:5]
	s_mul_i32 s5, s20, 0x1200
	s_mul_hi_i32 s4, s20, 0x1200
	s_add_u32 s5, s34, s5
	s_addc_u32 s4, s35, s4
	s_add_u32 s72, s5, 0x11380000
	s_addc_u32 s73, s4, 0
	s_mul_i32 s4, s20, 0x500
	s_mul_hi_i32 s5, s20, 0x500
	s_add_u32 s4, s34, s4
	s_addc_u32 s5, s35, s5
	v_lshl_add_u64 v[18:19], s[4:5], 0, v[18:19]
	s_mov_b64 s[4:5], 0x16480400
	v_lshl_add_u64 v[84:85], v[18:19], 0, s[4:5]
	v_and_b32_e32 v18, 15, v198
	v_mul_f32_e32 v70, v36, v28
	v_ldexp_f32 v116, v22, v23
	v_cmp_gt_u32_e64 s[44:45], 4, v27
	v_add_u32_e32 v118, -6, v38
	v_cmp_gt_i32_e64 s[48:49], 16, v198
	v_cmp_gt_u32_e64 s[50:51], 2, v26
	v_cmp_gt_i32_e64 s[54:55], 24, v198
	v_ashrrev_i32_e32 v74, 2, v198
	v_xor_b32_e32 v119, 4, v34
	v_xor_b32_e32 v120, 8, v34
	v_xor_b32_e32 v121, 16, v34
	v_xor_b32_e32 v122, 32, v34
	v_xor_b32_e32 v123, 64, v34
	v_xor_b32_e32 v124, 0x80, v34
	v_cmp_lt_i32_e64 s[56:57], 47, v198
	s_mov_b32 s21, s6
	s_mul_hi_i32 s65, s36, 0x500
	s_mul_i32 s64, s36, 0x500
	v_lshl_or_b32 v86, v26, 4, v248
	v_mov_b32_e32 v87, v1
	v_lshlrev_b32_e32 v88, 4, v18
	v_mov_b32_e32 v89, v1
	s_mov_b32 s4, s20
	v_lshl_add_u64 v[176:177], s[72:73], 0, v[82:83]
	v_lshl_add_u64 v[178:179], s[72:73], 0, v[88:89]
	global_load_dwordx4 v[158:161], v[176:177], off offset:-2816
	global_load_dwordx4 v[142:145], v[176:177], off
	global_load_dwordx4 v[154:157], v[178:179], off offset:1024
	global_load_dwordx4 v[146:149], v[178:179], off offset:3840
	v_lshl_add_u64 v[180:181], s[72:73], 0, v[86:87]
	v_lshl_add_u64 v[182:183], s[72:73], 0, v[78:79]
	global_load_dwordx4 v[150:153], v[180:181], off
	global_load_dwordx2 v[164:165], v[182:183], off offset:1280
	global_load_dwordx2 v[166:167], v[182:183], off offset:2304
	global_load_dwordx2 v[162:163], v[182:183], off offset:1792
	s_cmpk_lt_i32 s4, 0x4000
	s_cselect_b32 s14, s90, 0xff
	s_and_b32 s11, s4, s14
	s_cmp_eq_u32 s11, 0
	s_cbranch_scc1 .Lf1p_prev_zero
	global_load_dwordx2 v[168:169], v[182:183], off offset:-3328
	global_load_dwordx2 v[170:171], v[182:183], off offset:-2304
	s_branch .Lf1p_prev_done

; __device__ __forceinline__ unsigned cvt_pk_bf16(float lo, float hi) { unsigned r; asm volatile("v_cvt_pk_bf16_f32 %0, %1, %2" : "=v"(r) : "v"(lo), "v"(hi)); return r; }
;     __device__ __forceinline__ void operator()(const f32x4 (&acc)[2][2][4][2], const Unit& u, int wr, int wc, int fr, int fq) const {
;     ...
;             for (int m = 0; m < 4; ++m) { bf16_t* rowp = base + (size_t)(row0 + ai * HALF + m * 16) * ldc + col0;
; #pragma unroll
;                 for (int bj = 0; bj < 2; ++bj) { f32x4 v0 = acc[ai][bj][m][0] + bv[bj][0], v1 = acc[ai][bj][m][1] + bv[bj][1];
;                     v0 = v0 * sc; v1 = v1 * sc; u32x4 w; w.x = cvt_pk_bf16(v0[0], v0[1]); w.y = cvt_pk_bf16(v0[2], v0[3]); w.z = cvt_pk_bf16(v1[0], v1[1]); w.w = cvt_pk_bf16(v1[2], v1[3]);
;                     if (!(ldc == 2304 && col0 + bj * HALF >= 2080) && !(ldc == 1536 && u.pn < 3 && wc == 3)) *(u32x4*)(rowp + bj * HALF) = w; } }
.LBB0_236:
	v_lshl_add_u32 v146, s78, 8, v142
	v_ashrrev_i32_e32 v127, 31, v126
	v_lshl_add_u64 v[128:129], v[126:127], 1, s[22:23]
	v_mad_i64_i32 v[140:141], s[70:71], v146, s4, 0
	v_lshl_add_u64 v[140:141], v[140:141], 1, v[128:129]
	s_and_saveexec_b64 s[70:71], s[64:65]
	s_cbranch_execz .LBB0_238
	global_store_dwordx4 v[140:141], v[122:125], off

; __device__ __forceinline__ unsigned cvt_pk_bf16(float lo, float hi) { unsigned r; asm volatile("v_cvt_pk_bf16_f32 %0, %1, %2" : "=v"(r) : "v"(lo), "v"(hi)); return r; }
;     __device__ __forceinline__ void operator()(const f32x4 (&acc)[2][2][4][2], const Unit& u, int wr, int wc, int fr, int fq) const {
;     ...
;             for (int m = 0; m < 4; ++m) { bf16_t* rowp = base + (size_t)(row0 + ai * HALF + m * 16) * ldc + col0;
; #pragma unroll
;                 for (int bj = 0; bj < 2; ++bj) { f32x4 v0 = acc[ai][bj][m][0] + bv[bj][0], v1 = acc[ai][bj][m][1] + bv[bj][1];
;                     v0 = v0 * sc; v1 = v1 * sc; u32x4 w; w.x = cvt_pk_bf16(v0[0], v0[1]); w.y = cvt_pk_bf16(v0[2], v0[3]); w.z = cvt_pk_bf16(v1[0], v1[1]); w.w = cvt_pk_bf16(v1[2], v1[3]);
;                     if (!(ldc == 2304 && col0 + bj * HALF >= 2080) && !(ldc == 1536 && u.pn < 3 && wc == 3)) *(u32x4*)(rowp + bj * HALF) = w; } }
.LBB0_245:
	s_and_saveexec_b64 s[70:71], s[64:65]
	s_cbranch_execz .LBB0_247
	global_store_dwordx4 v[140:141], v[114:117], off offset:256

; __device__ __forceinline__ unsigned cvt_pk_bf16(float lo, float hi) { unsigned r; asm volatile("v_cvt_pk_bf16_f32 %0, %1, %2" : "=v"(r) : "v"(lo), "v"(hi)); return r; }
;     __device__ __forceinline__ void operator()(const f32x4 (&acc)[2][2][4][2], const Unit& u, int wr, int wc, int fr, int fq) const {
;     ...
;             for (int m = 0; m < 4; ++m) { bf16_t* rowp = base + (size_t)(row0 + ai * HALF + m * 16) * ldc + col0;
; #pragma unroll
;                 for (int bj = 0; bj < 2; ++bj) { f32x4 v0 = acc[ai][bj][m][0] + bv[bj][0], v1 = acc[ai][bj][m][1] + bv[bj][1];
;                     v0 = v0 * sc; v1 = v1 * sc; u32x4 w; w.x = cvt_pk_bf16(v0[0], v0[1]); w.y = cvt_pk_bf16(v0[2], v0[3]); w.z = cvt_pk_bf16(v1[0], v1[1]); w.w = cvt_pk_bf16(v1[2], v1[3]);
;                     if (!(ldc == 2304 && col0 + bj * HALF >= 2080) && !(ldc == 1536 && u.pn < 3 && wc == 3)) *(u32x4*)(rowp + bj * HALF) = w; } }
.LBB0_254:
	v_or_b32_e32 v110, 16, v146
	v_mad_i64_i32 v[110:111], s[70:71], v110, s4, 0
	v_lshl_add_u64 v[110:111], v[110:111], 1, v[128:129]
	s_and_saveexec_b64 s[70:71], s[64:65]
	s_cbranch_execz .LBB0_256
	global_store_dwordx4 v[110:111], v[106:109], off

; __device__ __forceinline__ unsigned cvt_pk_bf16(float lo, float hi) { unsigned r; asm volatile("v_cvt_pk_bf16_f32 %0, %1, %2" : "=v"(r) : "v"(lo), "v"(hi)); return r; }
;     __device__ __forceinline__ void operator()(const f32x4 (&acc)[2][2][4][2], const Unit& u, int wr, int wc, int fr, int fq) const {
;     ...
;             for (int m = 0; m < 4; ++m) { bf16_t* rowp = base + (size_t)(row0 + ai * HALF + m * 16) * ldc + col0;
; #pragma unroll
;                 for (int bj = 0; bj < 2; ++bj) { f32x4 v0 = acc[ai][bj][m][0] + bv[bj][0], v1 = acc[ai][bj][m][1] + bv[bj][1];
;                     v0 = v0 * sc; v1 = v1 * sc; u32x4 w; w.x = cvt_pk_bf16(v0[0], v0[1]); w.y = cvt_pk_bf16(v0[2], v0[3]); w.z = cvt_pk_bf16(v1[0], v1[1]); w.w = cvt_pk_bf16(v1[2], v1[3]);
;                     if (!(ldc == 2304 && col0 + bj * HALF >= 2080) && !(ldc == 1536 && u.pn < 3 && wc == 3)) *(u32x4*)(rowp + bj * HALF) = w; } }
.LBB0_263:
	s_and_saveexec_b64 s[70:71], s[64:65]
	s_cbranch_execz .LBB0_265
	global_store_dwordx4 v[110:111], v[98:101], off offset:256

; __device__ __forceinline__ unsigned cvt_pk_bf16(float lo, float hi) { unsigned r; asm volatile("v_cvt_pk_bf16_f32 %0, %1, %2" : "=v"(r) : "v"(lo), "v"(hi)); return r; }
;     __device__ __forceinline__ void operator()(const f32x4 (&acc)[2][2][4][2], const Unit& u, int wr, int wc, int fr, int fq) const {
;     ...
;             for (int m = 0; m < 4; ++m) { bf16_t* rowp = base + (size_t)(row0 + ai * HALF + m * 16) * ldc + col0;
; #pragma unroll
;                 for (int bj = 0; bj < 2; ++bj) { f32x4 v0 = acc[ai][bj][m][0] + bv[bj][0], v1 = acc[ai][bj][m][1] + bv[bj][1];
;                     v0 = v0 * sc; v1 = v1 * sc; u32x4 w; w.x = cvt_pk_bf16(v0[0], v0[1]); w.y = cvt_pk_bf16(v0[2], v0[3]); w.z = cvt_pk_bf16(v1[0], v1[1]); w.w = cvt_pk_bf16(v1[2], v1[3]);
;                     if (!(ldc == 2304 && col0 + bj * HALF >= 2080) && !(ldc == 1536 && u.pn < 3 && wc == 3)) *(u32x4*)(rowp + bj * HALF) = w; } }
.LBB0_272:
	v_or_b32_e32 v94, 32, v146
	v_mad_i64_i32 v[94:95], s[70:71], v94, s4, 0
	v_lshl_add_u64 v[94:95], v[94:95], 1, v[128:129]
	s_and_saveexec_b64 s[70:71], s[64:65]
	s_cbranch_execz .LBB0_274
	global_store_dwordx4 v[94:95], v[90:93], off

; __device__ __forceinline__ unsigned cvt_pk_bf16(float lo, float hi) { unsigned r; asm volatile("v_cvt_pk_bf16_f32 %0, %1, %2" : "=v"(r) : "v"(lo), "v"(hi)); return r; }
;     __device__ __forceinline__ void operator()(const f32x4 (&acc)[2][2][4][2], const Unit& u, int wr, int wc, int fr, int fq) const {
;     ...
;             for (int m = 0; m < 4; ++m) { bf16_t* rowp = base + (size_t)(row0 + ai * HALF + m * 16) * ldc + col0;
; #pragma unroll
;                 for (int bj = 0; bj < 2; ++bj) { f32x4 v0 = acc[ai][bj][m][0] + bv[bj][0], v1 = acc[ai][bj][m][1] + bv[bj][1];
;                     v0 = v0 * sc; v1 = v1 * sc; u32x4 w; w.x = cvt_pk_bf16(v0[0], v0[1]); w.y = cvt_pk_bf16(v0[2], v0[3]); w.z = cvt_pk_bf16(v1[0], v1[1]); w.w = cvt_pk_bf16(v1[2], v1[3]);
;                     if (!(ldc == 2304 && col0 + bj * HALF >= 2080) && !(ldc == 1536 && u.pn < 3 && wc == 3)) *(u32x4*)(rowp + bj * HALF) = w; } }
.LBB0_281:
	s_and_saveexec_b64 s[70:71], s[64:65]
	s_cbranch_execz .LBB0_283
	global_store_dwordx4 v[94:95], v[82:85], off offset:256

; __device__ __forceinline__ unsigned cvt_pk_bf16(float lo, float hi) { unsigned r; asm volatile("v_cvt_pk_bf16_f32 %0, %1, %2" : "=v"(r) : "v"(lo), "v"(hi)); return r; }
;     __device__ __forceinline__ void operator()(const f32x4 (&acc)[2][2][4][2], const Unit& u, int wr, int wc, int fr, int fq) const {
;     ...
;             for (int m = 0; m < 4; ++m) { bf16_t* rowp = base + (size_t)(row0 + ai * HALF + m * 16) * ldc + col0;
; #pragma unroll
;                 for (int bj = 0; bj < 2; ++bj) { f32x4 v0 = acc[ai][bj][m][0] + bv[bj][0], v1 = acc[ai][bj][m][1] + bv[bj][1];
;                     v0 = v0 * sc; v1 = v1 * sc; u32x4 w; w.x = cvt_pk_bf16(v0[0], v0[1]); w.y = cvt_pk_bf16(v0[2], v0[3]); w.z = cvt_pk_bf16(v1[0], v1[1]); w.w = cvt_pk_bf16(v1[2], v1[3]);
;                     if (!(ldc == 2304 && col0 + bj * HALF >= 2080) && !(ldc == 1536 && u.pn < 3 && wc == 3)) *(u32x4*)(rowp + bj * HALF) = w; } }
.LBB0_290:
	v_or_b32_e32 v78, 48, v146
	v_mad_i64_i32 v[78:79], s[70:71], v78, s4, 0
	v_lshl_add_u64 v[78:79], v[78:79], 1, v[128:129]
	s_and_saveexec_b64 s[70:71], s[64:65]
	s_cbranch_execz .LBB0_292
	global_store_dwordx4 v[78:79], v[74:77], off

; __device__ __forceinline__ unsigned cvt_pk_bf16(float lo, float hi) { unsigned r; asm volatile("v_cvt_pk_bf16_f32 %0, %1, %2" : "=v"(r) : "v"(lo), "v"(hi)); return r; }
;     __device__ __forceinline__ void operator()(const f32x4 (&acc)[2][2][4][2], const Unit& u, int wr, int wc, int fr, int fq) const {
;     ...
;             for (int m = 0; m < 4; ++m) { bf16_t* rowp = base + (size_t)(row0 + ai * HALF + m * 16) * ldc + col0;
; #pragma unroll
;                 for (int bj = 0; bj < 2; ++bj) { f32x4 v0 = acc[ai][bj][m][0] + bv[bj][0], v1 = acc[ai][bj][m][1] + bv[bj][1];
;                     v0 = v0 * sc; v1 = v1 * sc; u32x4 w; w.x = cvt_pk_bf16(v0[0], v0[1]); w.y = cvt_pk_bf16(v0[2], v0[3]); w.z = cvt_pk_bf16(v1[0], v1[1]); w.w = cvt_pk_bf16(v1[2], v1[3]);
;                     if (!(ldc == 2304 && col0 + bj * HALF >= 2080) && !(ldc == 1536 && u.pn < 3 && wc == 3)) *(u32x4*)(rowp + bj * HALF) = w; } }
.LBB0_299:
	s_and_saveexec_b64 s[70:71], s[64:65]
	s_cbranch_execz .LBB0_301
	global_store_dwordx4 v[78:79], v[66:69], off offset:256

; __device__ __forceinline__ unsigned cvt_pk_bf16(float lo, float hi) { unsigned r; asm volatile("v_cvt_pk_bf16_f32 %0, %1, %2" : "=v"(r) : "v"(lo), "v"(hi)); return r; }
;     __device__ __forceinline__ void operator()(const f32x4 (&acc)[2][2][4][2], const Unit& u, int wr, int wc, int fr, int fq) const {
;     ...
;             for (int m = 0; m < 4; ++m) { bf16_t* rowp = base + (size_t)(row0 + ai * HALF + m * 16) * ldc + col0;
; #pragma unroll
;                 for (int bj = 0; bj < 2; ++bj) { f32x4 v0 = acc[ai][bj][m][0] + bv[bj][0], v1 = acc[ai][bj][m][1] + bv[bj][1];
;                     v0 = v0 * sc; v1 = v1 * sc; u32x4 w; w.x = cvt_pk_bf16(v0[0], v0[1]); w.y = cvt_pk_bf16(v0[2], v0[3]); w.z = cvt_pk_bf16(v1[0], v1[1]); w.w = cvt_pk_bf16(v1[2], v1[3]);
;                     if (!(ldc == 2304 && col0 + bj * HALF >= 2080) && !(ldc == 1536 && u.pn < 3 && wc == 3)) *(u32x4*)(rowp + bj * HALF) = w; } }
.LBB0_308:
	v_add_u32_e32 v62, 0x80, v146
	v_mad_i64_i32 v[62:63], s[70:71], v62, s4, 0
	v_lshl_add_u64 v[62:63], v[62:63], 1, v[128:129]
	s_and_saveexec_b64 s[70:71], s[64:65]
	s_cbranch_execz .LBB0_310
	global_store_dwordx4 v[62:63], v[58:61], off

; __device__ __forceinline__ unsigned cvt_pk_bf16(float lo, float hi) { unsigned r; asm volatile("v_cvt_pk_bf16_f32 %0, %1, %2" : "=v"(r) : "v"(lo), "v"(hi)); return r; }
;     __device__ __forceinline__ void operator()(const f32x4 (&acc)[2][2][4][2], const Unit& u, int wr, int wc, int fr, int fq) const {
;     ...
;             for (int m = 0; m < 4; ++m) { bf16_t* rowp = base + (size_t)(row0 + ai * HALF + m * 16) * ldc + col0;
; #pragma unroll
;                 for (int bj = 0; bj < 2; ++bj) { f32x4 v0 = acc[ai][bj][m][0] + bv[bj][0], v1 = acc[ai][bj][m][1] + bv[bj][1];
;                     v0 = v0 * sc; v1 = v1 * sc; u32x4 w; w.x = cvt_pk_bf16(v0[0], v0[1]); w.y = cvt_pk_bf16(v0[2], v0[3]); w.z = cvt_pk_bf16(v1[0], v1[1]); w.w = cvt_pk_bf16(v1[2], v1[3]);
;                     if (!(ldc == 2304 && col0 + bj * HALF >= 2080) && !(ldc == 1536 && u.pn < 3 && wc == 3)) *(u32x4*)(rowp + bj * HALF) = w; } }
.LBB0_317:
	s_and_saveexec_b64 s[70:71], s[64:65]
	s_cbranch_execz .LBB0_319
	global_store_dwordx4 v[62:63], v[50:53], off offset:256

; __device__ __forceinline__ unsigned cvt_pk_bf16(float lo, float hi) { unsigned r; asm volatile("v_cvt_pk_bf16_f32 %0, %1, %2" : "=v"(r) : "v"(lo), "v"(hi)); return r; }
;     __device__ __forceinline__ void operator()(const f32x4 (&acc)[2][2][4][2], const Unit& u, int wr, int wc, int fr, int fq) const {
;     ...
;             for (int m = 0; m < 4; ++m) { bf16_t* rowp = base + (size_t)(row0 + ai * HALF + m * 16) * ldc + col0;
; #pragma unroll
;                 for (int bj = 0; bj < 2; ++bj) { f32x4 v0 = acc[ai][bj][m][0] + bv[bj][0], v1 = acc[ai][bj][m][1] + bv[bj][1];
;                     v0 = v0 * sc; v1 = v1 * sc; u32x4 w; w.x = cvt_pk_bf16(v0[0], v0[1]); w.y = cvt_pk_bf16(v0[2], v0[3]); w.z = cvt_pk_bf16(v1[0], v1[1]); w.w = cvt_pk_bf16(v1[2], v1[3]);
;                     if (!(ldc == 2304 && col0 + bj * HALF >= 2080) && !(ldc == 1536 && u.pn < 3 && wc == 3)) *(u32x4*)(rowp + bj * HALF) = w; } }
.LBB0_326:
	v_add_u32_e32 v46, 0x90, v146
	v_mad_i64_i32 v[46:47], s[70:71], v46, s4, 0
	v_lshl_add_u64 v[46:47], v[46:47], 1, v[128:129]
	s_and_saveexec_b64 s[70:71], s[64:65]
	s_cbranch_execz .LBB0_328
	global_store_dwordx4 v[46:47], v[42:45], off

; __device__ __forceinline__ unsigned cvt_pk_bf16(float lo, float hi) { unsigned r; asm volatile("v_cvt_pk_bf16_f32 %0, %1, %2" : "=v"(r) : "v"(lo), "v"(hi)); return r; }
;     __device__ __forceinline__ void operator()(const f32x4 (&acc)[2][2][4][2], const Unit& u, int wr, int wc, int fr, int fq) const {
;     ...
;             for (int m = 0; m < 4; ++m) { bf16_t* rowp = base + (size_t)(row0 + ai * HALF + m * 16) * ldc + col0;
; #pragma unroll
;                 for (int bj = 0; bj < 2; ++bj) { f32x4 v0 = acc[ai][bj][m][0] + bv[bj][0], v1 = acc[ai][bj][m][1] + bv[bj][1];
;                     v0 = v0 * sc; v1 = v1 * sc; u32x4 w; w.x = cvt_pk_bf16(v0[0], v0[1]); w.y = cvt_pk_bf16(v0[2], v0[3]); w.z = cvt_pk_bf16(v1[0], v1[1]); w.w = cvt_pk_bf16(v1[2], v1[3]);
;                     if (!(ldc == 2304 && col0 + bj * HALF >= 2080) && !(ldc == 1536 && u.pn < 3 && wc == 3)) *(u32x4*)(rowp + bj * HALF) = w; } }
.LBB0_335:
	s_and_saveexec_b64 s[70:71], s[64:65]
	s_cbranch_execz .LBB0_337
	global_store_dwordx4 v[46:47], v[34:37], off offset:256

; __device__ __forceinline__ unsigned cvt_pk_bf16(float lo, float hi) { unsigned r; asm volatile("v_cvt_pk_bf16_f32 %0, %1, %2" : "=v"(r) : "v"(lo), "v"(hi)); return r; }
;     __device__ __forceinline__ void operator()(const f32x4 (&acc)[2][2][4][2], const Unit& u, int wr, int wc, int fr, int fq) const {
;     ...
;             for (int m = 0; m < 4; ++m) { bf16_t* rowp = base + (size_t)(row0 + ai * HALF + m * 16) * ldc + col0;
; #pragma unroll
;                 for (int bj = 0; bj < 2; ++bj) { f32x4 v0 = acc[ai][bj][m][0] + bv[bj][0], v1 = acc[ai][bj][m][1] + bv[bj][1];
;                     v0 = v0 * sc; v1 = v1 * sc; u32x4 w; w.x = cvt_pk_bf16(v0[0], v0[1]); w.y = cvt_pk_bf16(v0[2], v0[3]); w.z = cvt_pk_bf16(v1[0], v1[1]); w.w = cvt_pk_bf16(v1[2], v1[3]);
;                     if (!(ldc == 2304 && col0 + bj * HALF >= 2080) && !(ldc == 1536 && u.pn < 3 && wc == 3)) *(u32x4*)(rowp + bj * HALF) = w; } }
.LBB0_344:
	v_add_u32_e32 v30, 0xa0, v146
	v_mad_i64_i32 v[30:31], s[70:71], v30, s4, 0
	v_lshl_add_u64 v[30:31], v[30:31], 1, v[128:129]
	s_and_saveexec_b64 s[70:71], s[64:65]
	s_cbranch_execz .LBB0_346
	global_store_dwordx4 v[30:31], v[26:29], off

; __device__ __forceinline__ unsigned cvt_pk_bf16(float lo, float hi) { unsigned r; asm volatile("v_cvt_pk_bf16_f32 %0, %1, %2" : "=v"(r) : "v"(lo), "v"(hi)); return r; }
;     __device__ __forceinline__ void operator()(const f32x4 (&acc)[2][2][4][2], const Unit& u, int wr, int wc, int fr, int fq) const {
;     ...
;             for (int m = 0; m < 4; ++m) { bf16_t* rowp = base + (size_t)(row0 + ai * HALF + m * 16) * ldc + col0;
; #pragma unroll
;                 for (int bj = 0; bj < 2; ++bj) { f32x4 v0 = acc[ai][bj][m][0] + bv[bj][0], v1 = acc[ai][bj][m][1] + bv[bj][1];
;                     v0 = v0 * sc; v1 = v1 * sc; u32x4 w; w.x = cvt_pk_bf16(v0[0], v0[1]); w.y = cvt_pk_bf16(v0[2], v0[3]); w.z = cvt_pk_bf16(v1[0], v1[1]); w.w = cvt_pk_bf16(v1[2], v1[3]);
;                     if (!(ldc == 2304 && col0 + bj * HALF >= 2080) && !(ldc == 1536 && u.pn < 3 && wc == 3)) *(u32x4*)(rowp + bj * HALF) = w; } }
.LBB0_353:
	s_and_saveexec_b64 s[70:71], s[64:65]
	s_cbranch_execz .LBB0_355
	global_store_dwordx4 v[30:31], v[18:21], off offset:256

; __device__ __forceinline__ unsigned cvt_pk_bf16(float lo, float hi) { unsigned r; asm volatile("v_cvt_pk_bf16_f32 %0, %1, %2" : "=v"(r) : "v"(lo), "v"(hi)); return r; }
;     __device__ __forceinline__ void operator()(const f32x4 (&acc)[2][2][4][2], const Unit& u, int wr, int wc, int fr, int fq) const {
;     ...
;             for (int m = 0; m < 4; ++m) { bf16_t* rowp = base + (size_t)(row0 + ai * HALF + m * 16) * ldc + col0;
; #pragma unroll
;                 for (int bj = 0; bj < 2; ++bj) { f32x4 v0 = acc[ai][bj][m][0] + bv[bj][0], v1 = acc[ai][bj][m][1] + bv[bj][1];
;                     v0 = v0 * sc; v1 = v1 * sc; u32x4 w; w.x = cvt_pk_bf16(v0[0], v0[1]); w.y = cvt_pk_bf16(v0[2], v0[3]); w.z = cvt_pk_bf16(v1[0], v1[1]); w.w = cvt_pk_bf16(v1[2], v1[3]);
;                     if (!(ldc == 2304 && col0 + bj * HALF >= 2080) && !(ldc == 1536 && u.pn < 3 && wc == 3)) *(u32x4*)(rowp + bj * HALF) = w; } }
.LBB0_362:
	v_add_u32_e32 v14, 0xb0, v146
	v_mad_i64_i32 v[14:15], s[70:71], v14, s4, 0
	v_lshl_add_u64 v[14:15], v[14:15], 1, v[128:129]
	s_and_saveexec_b64 s[70:71], s[64:65]
	s_cbranch_execz .LBB0_364
	global_store_dwordx4 v[14:15], v[10:13], off

; __device__ __forceinline__ unsigned cvt_pk_bf16(float lo, float hi) { unsigned r; asm volatile("v_cvt_pk_bf16_f32 %0, %1, %2" : "=v"(r) : "v"(lo), "v"(hi)); return r; }
;     __device__ __forceinline__ void operator()(const f32x4 (&acc)[2][2][4][2], const Unit& u, int wr, int wc, int fr, int fq) const {
;     ...
;             for (int m = 0; m < 4; ++m) { bf16_t* rowp = base + (size_t)(row0 + ai * HALF + m * 16) * ldc + col0;
; #pragma unroll
;                 for (int bj = 0; bj < 2; ++bj) { f32x4 v0 = acc[ai][bj][m][0] + bv[bj][0], v1 = acc[ai][bj][m][1] + bv[bj][1];
;                     v0 = v0 * sc; v1 = v1 * sc; u32x4 w; w.x = cvt_pk_bf16(v0[0], v0[1]); w.y = cvt_pk_bf16(v0[2], v0[3]); w.z = cvt_pk_bf16(v1[0], v1[1]); w.w = cvt_pk_bf16(v1[2], v1[3]);
;                     if (!(ldc == 2304 && col0 + bj * HALF >= 2080) && !(ldc == 1536 && u.pn < 3 && wc == 3)) *(u32x4*)(rowp + bj * HALF) = w; } }
.LBB0_371:
	s_and_saveexec_b64 s[70:71], s[64:65]
	s_cbranch_execz .LBB0_373
	global_store_dwordx4 v[14:15], v[2:5], off offset:256

; __device__ __forceinline__ unsigned cvt_pk_bf16(float lo, float hi) { unsigned r; asm volatile("v_cvt_pk_bf16_f32 %0, %1, %2" : "=v"(r) : "v"(lo), "v"(hi)); return r; }
;     __device__ __forceinline__ void operator()(const f32x4 (&acc)[2][2][4][2], const Unit& u, int wr, int wc, int fr, int fq) const {
;         const int rowt = u.pm * BM; const int mr = rowt < MLAT ? (rowt >> 11) : 8;
;         const float* gv = modl + (size_t)mr * (NMOD * DM) + kmod * DM;
;         const int col0 = u.pn * BM + wc * 32 + 8 * fq;
;         f32x4 g[2][2];
; #pragma unroll
;         for (int bj = 0; bj < 2; ++bj)
; #pragma unroll
;             for (int n = 0; n < 2; ++n) g[bj][n] = *(const f32x4*)(gv + col0 + bj * HALF + 4 * n) * coef;
;         float* part = (float*)((char*)const_cast<bf16_t*>(xin) + ((long long)WS_PART - (long long)WS_X));
;         if (u.ntk != (kmod == 5 ? DM / 64 : DFF / 64)) {
; #pragma unroll
;             for (int ai = 0; ai < 2; ++ai)
; #pragma unroll
;                 for (int m = 0; m < 4; ++m) {
;                     bf16_t* pp = (bf16_t*)part + ((size_t)u.part * MCTX + (rowt - MLAT + ai * HALF + wr * 64 + m * 16 + fr)) * DM + col0;
; #pragma unroll
;                     for (int bj = 0; bj < 2; ++bj) { const f32x4 y0 = g[bj][0] * acc[ai][bj][m][0], y1 = g[bj][1] * acc[ai][bj][m][1];
;                         u32x4 o; o.x = cvt_pk_bf16(y0[0], y0[1]); o.y = cvt_pk_bf16(y0[2], y0[3]); o.z = cvt_pk_bf16(y1[0], y1[1]); o.w = cvt_pk_bf16(y1[2], y1[3]); *(u32x4*)(pp + bj * HALF) = o; }
;                 }
;             return;
.LBB0_441:
	s_min_i32 s13, s15, 64
	s_ashr_i32 s13, s13, 3
	s_mul_hi_i32 s14, s13, 0x9000
	s_mul_i32 s13, s13, 0x9000
	s_add_u32 s64, s5, s13
	v_lshl_or_b32 v176, s43, 8, v209
	s_addc_u32 s65, s6, s14
	v_ashrrev_i32_e32 v177, 31, v176
	v_lshl_add_u64 v[142:143], v[176:177], 2, s[64:65]
	global_load_dwordx4 v[130:133], v[142:143], off
	global_load_dwordx4 v[134:137], v[142:143], off offset:16
	global_load_dwordx4 v[138:141], v[142:143], off offset:512
	s_nop 0
	global_load_dwordx4 v[142:145], v[142:143], off offset:528
	s_lshl_b32 s15, s15, 8
	s_cmp_eq_u32 s86, s7
	s_mov_b64 s[64:65], -1
	s_waitcnt vmcnt(0) lgkmcnt(0)
	v_pk_mul_f32 v[184:185], s[58:59], v[132:133]
	v_pk_mul_f32 v[182:183], s[48:49], v[130:131]
	v_pk_mul_f32 v[180:181], s[58:59], v[136:137]
	v_pk_mul_f32 v[178:179], s[48:49], v[134:135]
	v_pk_mul_f32 v[174:175], s[58:59], v[140:141]
	v_pk_mul_f32 v[172:173], s[48:49], v[138:139]
	v_pk_mul_f32 v[170:171], s[58:59], v[144:145]
	v_pk_mul_f32 v[168:169], s[48:49], v[142:143]
	s_cbranch_scc1 .LBB0_447
	s_ashr_i32 s43, s42, 31
	v_add_u32_e32 v130, s15, v208
	s_lshl_b64 s[42:43], s[42:43], 22
	v_ashrrev_i32_e32 v131, 31, v130
	s_add_u32 s42, s8, s42
	s_addc_u32 s43, s9, s43
	v_lshlrev_b64 v[132:133], 11, v[130:131]
	v_lshl_add_u64 v[134:135], s[42:43], 0, v[132:133]
	v_lshlrev_b64 v[132:133], 1, v[176:177]
	v_lshl_add_u64 v[138:139], v[134:135], 0, v[132:133]
	v_pk_mul_f32 v[134:135], v[126:127], v[182:183]
	v_pk_mul_f32 v[136:137], v[128:129], v[184:185]
	v_cvt_pk_bf16_f32 v134, v134, v135
	v_pk_mul_f32 v[140:141], v[124:125], v[180:181]
	v_cvt_pk_bf16_f32 v135, v136, v137
	v_pk_mul_f32 v[142:143], v[122:123], v[178:179]
	s_nop 0
	v_cvt_pk_bf16_f32 v136, v142, v143
	v_cvt_pk_bf16_f32 v137, v140, v141
	global_store_dwordx4 v[138:139], v[134:137], off
	v_pk_mul_f32 v[140:141], v[116:117], v[170:171]
	v_pk_mul_f32 v[142:143], v[114:115], v[168:169]
	v_pk_mul_f32 v[134:135], v[118:119], v[172:173]
	v_pk_mul_f32 v[136:137], v[120:121], v[174:175]
	v_cvt_pk_bf16_f32 v134, v134, v135
	s_nop 0
	v_cvt_pk_bf16_f32 v135, v136, v137
	v_cvt_pk_bf16_f32 v136, v142, v143
	v_cvt_pk_bf16_f32 v137, v140, v141
	global_store_dwordx4 v[138:139], v[134:137], off offset:256
	v_pk_mul_f32 v[140:141], v[108:109], v[180:181]
	v_pk_mul_f32 v[142:143], v[106:107], v[178:179]
	v_or_b32_e32 v134, 16, v130
	v_ashrrev_i32_e32 v135, 31, v134
	v_lshlrev_b64 v[134:135], 11, v[134:135]
	v_lshl_add_u64 v[134:135], s[42:43], 0, v[134:135]
	v_lshl_add_u64 v[138:139], v[134:135], 0, v[132:133]
	v_pk_mul_f32 v[134:135], v[110:111], v[182:183]
	v_pk_mul_f32 v[136:137], v[112:113], v[184:185]
	v_cvt_pk_bf16_f32 v134, v134, v135
	s_nop 0
	v_cvt_pk_bf16_f32 v135, v136, v137
	v_cvt_pk_bf16_f32 v136, v142, v143
	v_cvt_pk_bf16_f32 v137, v140, v141
	global_store_dwordx4 v[138:139], v[134:137], off
	v_pk_mul_f32 v[140:141], v[100:101], v[170:171]
	v_pk_mul_f32 v[142:143], v[98:99], v[168:169]
	v_pk_mul_f32 v[134:135], v[102:103], v[172:173]
	v_pk_mul_f32 v[136:137], v[104:105], v[174:175]
	v_cvt_pk_bf16_f32 v134, v134, v135
	s_nop 0
	v_cvt_pk_bf16_f32 v135, v136, v137
	v_cvt_pk_bf16_f32 v136, v142, v143
	v_cvt_pk_bf16_f32 v137, v140, v141
	global_store_dwordx4 v[138:139], v[134:137], off offset:256
	v_pk_mul_f32 v[140:141], v[92:93], v[180:181]
	v_pk_mul_f32 v[142:143], v[90:91], v[178:179]
	v_or_b32_e32 v134, 32, v130
	v_ashrrev_i32_e32 v135, 31, v134
	v_lshlrev_b64 v[134:135], 11, v[134:135]
	v_lshl_add_u64 v[134:135], s[42:43], 0, v[134:135]
	v_lshl_add_u64 v[138:139], v[134:135], 0, v[132:133]
	v_pk_mul_f32 v[134:135], v[94:95], v[182:183]
	v_pk_mul_f32 v[136:137], v[96:97], v[184:185]
	v_cvt_pk_bf16_f32 v134, v134, v135
	s_nop 0
	v_cvt_pk_bf16_f32 v135, v136, v137
	v_cvt_pk_bf16_f32 v136, v142, v143
	v_cvt_pk_bf16_f32 v137, v140, v141
	global_store_dwordx4 v[138:139], v[134:137], off
	v_pk_mul_f32 v[140:141], v[84:85], v[170:171]
	v_pk_mul_f32 v[142:143], v[82:83], v[168:169]
	v_pk_mul_f32 v[134:135], v[86:87], v[172:173]
	v_pk_mul_f32 v[136:137], v[88:89], v[174:175]
	v_cvt_pk_bf16_f32 v134, v134, v135
	s_nop 0
	v_cvt_pk_bf16_f32 v135, v136, v137
	v_cvt_pk_bf16_f32 v136, v142, v143
	v_cvt_pk_bf16_f32 v137, v140, v141
	global_store_dwordx4 v[138:139], v[134:137], off offset:256
	v_pk_mul_f32 v[140:141], v[76:77], v[180:181]
	v_pk_mul_f32 v[142:143], v[74:75], v[178:179]
	v_or_b32_e32 v134, 48, v130
	v_ashrrev_i32_e32 v135, 31, v134
	v_lshlrev_b64 v[134:135], 11, v[134:135]
	v_lshl_add_u64 v[134:135], s[42:43], 0, v[134:135]
	v_lshl_add_u64 v[138:139], v[134:135], 0, v[132:133]
	v_pk_mul_f32 v[134:135], v[78:79], v[182:183]
	v_pk_mul_f32 v[136:137], v[80:81], v[184:185]
; __device__ __forceinline__ unsigned cvt_pk_bf16(float lo, float hi) { unsigned r; asm volatile("v_cvt_pk_bf16_f32 %0, %1, %2" : "=v"(r) : "v"(lo), "v"(hi)); return r; }
;     __device__ __forceinline__ void operator()(const f32x4 (&acc)[2][2][4][2], const Unit& u, int wr, int wc, int fr, int fq) const {
;     ...
;             for (int ai = 0; ai < 2; ++ai)
; #pragma unroll
;                 for (int m = 0; m < 4; ++m) {
;                     bf16_t* pp = (bf16_t*)part + ((size_t)u.part * MCTX + (rowt - MLAT + ai * HALF + wr * 64 + m * 16 + fr)) * DM + col0;
; #pragma unroll
;                     for (int bj = 0; bj < 2; ++bj) { const f32x4 y0 = g[bj][0] * acc[ai][bj][m][0], y1 = g[bj][1] * acc[ai][bj][m][1];
;                         u32x4 o; o.x = cvt_pk_bf16(y0[0], y0[1]); o.y = cvt_pk_bf16(y0[2], y0[3]); o.z = cvt_pk_bf16(y1[0], y1[1]); o.w = cvt_pk_bf16(y1[2], y1[3]); *(u32x4*)(pp + bj * HALF) = o; }
;                 }
;             return;
	v_cvt_pk_bf16_f32 v134, v134, v135
	s_nop 0
	v_cvt_pk_bf16_f32 v135, v136, v137
	v_cvt_pk_bf16_f32 v136, v142, v143
	v_cvt_pk_bf16_f32 v137, v140, v141
	global_store_dwordx4 v[138:139], v[134:137], off
	v_pk_mul_f32 v[140:141], v[68:69], v[170:171]
	v_pk_mul_f32 v[142:143], v[66:67], v[168:169]
	v_pk_mul_f32 v[134:135], v[70:71], v[172:173]
	v_pk_mul_f32 v[136:137], v[72:73], v[174:175]
	v_cvt_pk_bf16_f32 v134, v134, v135
	s_nop 0
	v_cvt_pk_bf16_f32 v135, v136, v137
	v_cvt_pk_bf16_f32 v136, v142, v143
	v_cvt_pk_bf16_f32 v137, v140, v141
	global_store_dwordx4 v[138:139], v[134:137], off offset:256
	v_pk_mul_f32 v[140:141], v[60:61], v[180:181]
	v_pk_mul_f32 v[142:143], v[58:59], v[178:179]
	v_add_u32_e32 v134, 0x80, v130
	v_ashrrev_i32_e32 v135, 31, v134
	v_lshlrev_b64 v[134:135], 11, v[134:135]
	v_lshl_add_u64 v[134:135], s[42:43], 0, v[134:135]
	v_lshl_add_u64 v[138:139], v[134:135], 0, v[132:133]
	v_pk_mul_f32 v[134:135], v[62:63], v[182:183]
	v_pk_mul_f32 v[136:137], v[64:65], v[184:185]
	v_cvt_pk_bf16_f32 v134, v134, v135
	s_nop 0
	v_cvt_pk_bf16_f32 v135, v136, v137
	v_cvt_pk_bf16_f32 v136, v142, v143
	v_cvt_pk_bf16_f32 v137, v140, v141
	global_store_dwordx4 v[138:139], v[134:137], off
	v_pk_mul_f32 v[140:141], v[52:53], v[170:171]
	v_pk_mul_f32 v[142:143], v[50:51], v[168:169]
	v_pk_mul_f32 v[134:135], v[54:55], v[172:173]
	v_pk_mul_f32 v[136:137], v[56:57], v[174:175]
	v_cvt_pk_bf16_f32 v134, v134, v135
	s_nop 0
	v_cvt_pk_bf16_f32 v135, v136, v137
	v_cvt_pk_bf16_f32 v136, v142, v143
	v_cvt_pk_bf16_f32 v137, v140, v141
	global_store_dwordx4 v[138:139], v[134:137], off offset:256
	v_pk_mul_f32 v[140:141], v[44:45], v[180:181]
	v_pk_mul_f32 v[142:143], v[42:43], v[178:179]
	v_add_u32_e32 v134, 0x90, v130
	v_ashrrev_i32_e32 v135, 31, v134
	v_lshlrev_b64 v[134:135], 11, v[134:135]
	v_lshl_add_u64 v[134:135], s[42:43], 0, v[134:135]
	v_lshl_add_u64 v[138:139], v[134:135], 0, v[132:133]
	v_pk_mul_f32 v[134:135], v[46:47], v[182:183]
	v_pk_mul_f32 v[136:137], v[48:49], v[184:185]
	v_cvt_pk_bf16_f32 v134, v134, v135
	s_nop 0
	v_cvt_pk_bf16_f32 v135, v136, v137
	v_cvt_pk_bf16_f32 v136, v142, v143
	v_cvt_pk_bf16_f32 v137, v140, v141
	global_store_dwordx4 v[138:139], v[134:137], off
	v_pk_mul_f32 v[140:141], v[36:37], v[170:171]
	v_pk_mul_f32 v[142:143], v[34:35], v[168:169]
	v_pk_mul_f32 v[134:135], v[38:39], v[172:173]
	v_pk_mul_f32 v[136:137], v[40:41], v[174:175]
	v_cvt_pk_bf16_f32 v134, v134, v135
	s_nop 0
	v_cvt_pk_bf16_f32 v135, v136, v137
	v_cvt_pk_bf16_f32 v136, v142, v143
	v_cvt_pk_bf16_f32 v137, v140, v141
	global_store_dwordx4 v[138:139], v[134:137], off offset:256
	v_pk_mul_f32 v[140:141], v[28:29], v[180:181]
	v_pk_mul_f32 v[142:143], v[26:27], v[178:179]
	v_add_u32_e32 v134, 0xa0, v130
	v_ashrrev_i32_e32 v135, 31, v134
	v_lshlrev_b64 v[134:135], 11, v[134:135]
	v_lshl_add_u64 v[134:135], s[42:43], 0, v[134:135]
	v_lshl_add_u64 v[138:139], v[134:135], 0, v[132:133]
	v_pk_mul_f32 v[134:135], v[30:31], v[182:183]
	v_add_u32_e32 v130, 0xb0, v130
	v_pk_mul_f32 v[136:137], v[32:33], v[184:185]
	v_cvt_pk_bf16_f32 v134, v134, v135
	v_ashrrev_i32_e32 v131, 31, v130
	v_cvt_pk_bf16_f32 v135, v136, v137
	v_cvt_pk_bf16_f32 v136, v142, v143
	v_cvt_pk_bf16_f32 v137, v140, v141
	global_store_dwordx4 v[138:139], v[134:137], off
	v_lshlrev_b64 v[130:131], 11, v[130:131]
	v_lshl_add_u64 v[130:131], s[42:43], 0, v[130:131]
	v_pk_mul_f32 v[134:135], v[22:23], v[172:173]
	v_pk_mul_f32 v[136:137], v[24:25], v[174:175]
	v_cvt_pk_bf16_f32 v134, v134, v135
	v_pk_mul_f32 v[140:141], v[20:21], v[170:171]
	v_cvt_pk_bf16_f32 v135, v136, v137
	v_pk_mul_f32 v[142:143], v[18:19], v[168:169]
	s_nop 0
	v_cvt_pk_bf16_f32 v136, v142, v143
	v_cvt_pk_bf16_f32 v137, v140, v141
	global_store_dwordx4 v[138:139], v[134:137], off offset:256
	v_pk_mul_f32 v[138:139], v[10:11], v[178:179]
	s_nop 0
	v_lshl_add_u64 v[134:135], v[130:131], 0, v[132:133]
	v_pk_mul_f32 v[132:133], v[16:17], v[184:185]
	v_pk_mul_f32 v[130:131], v[14:15], v[182:183]
	v_pk_mul_f32 v[136:137], v[12:13], v[180:181]
	v_cvt_pk_bf16_f32 v130, v130, v131
	v_cvt_pk_bf16_f32 v131, v132, v133
	v_cvt_pk_bf16_f32 v132, v138, v139
	v_pk_mul_f32 v[138:139], v[2:3], v[168:169]
	v_cvt_pk_bf16_f32 v133, v136, v137
	global_store_dwordx4 v[134:135], v[130:133], off
	v_pk_mul_f32 v[136:137], v[4:5], v[170:171]
	s_nop 0
	v_pk_mul_f32 v[132:133], v[8:9], v[174:175]
	v_pk_mul_f32 v[130:131], v[6:7], v[172:173]
	s_nop 0
	v_cvt_pk_bf16_f32 v130, v130, v131
	v_cvt_pk_bf16_f32 v131, v132, v133
	v_cvt_pk_bf16_f32 v132, v138, v139
	v_cvt_pk_bf16_f32 v133, v136, v137
	global_store_dwordx4 v[134:135], v[130:133], off offset:256
	s_cbranch_execz .LBB0_448

; __device__ __forceinline__ unsigned cvt_pk_bf16(float lo, float hi) { unsigned r; asm volatile("v_cvt_pk_bf16_f32 %0, %1, %2" : "=v"(r) : "v"(lo), "v"(hi)); return r; }
;     __device__ __forceinline__ void operator()(const f32x4 (&acc)[2][2][4][2], const Unit& u, int wr, int wc, int fr, int fq) const {
;     ...
; #pragma unroll
;         for (int ai = 0; ai < 2; ++ai) {
;             u32x4 xb[4][2];
; #pragma unroll
;             for (int m = 0; m < 4; ++m)
; #pragma unroll
;                 for (int bj = 0; bj < 2; ++bj) xb[m][bj] = *(const u32x4*)(xin + (size_t)(rowt + ai * HALF + wr * 64 + m * 16 + fr) * DM + col0 + bj * HALF);
; #pragma unroll
;             for (int m = 0; m < 4; ++m) {
;                 const size_t off = (size_t)(rowt + ai * HALF + wr * 64 + m * 16 + fr) * DM + col0;
; #pragma unroll
;                 for (int bj = 0; bj < 2; ++bj) {
;                     const u32x4 x = xb[m][bj];
;                     const f32x4 x0 = {__builtin_bit_cast(float, x.x << 16), __builtin_bit_cast(float, x.x & 0xffff0000u), __builtin_bit_cast(float, x.y << 16), __builtin_bit_cast(float, x.y & 0xffff0000u)};
;                     const f32x4 x1 = {__builtin_bit_cast(float, x.z << 16), __builtin_bit_cast(float, x.z & 0xffff0000u), __builtin_bit_cast(float, x.w << 16), __builtin_bit_cast(float, x.w & 0xffff0000u)};
;                     const f32x4 y0 = x0 + g[bj][0] * acc[ai][bj][m][0], y1 = x1 + g[bj][1] * acc[ai][bj][m][1];
;                     if (fout) { *(f32x4*)(fout + off + bj * HALF) = y0; *(f32x4*)(fout + off + bj * HALF + 4) = y1; }
;                     else { u32x4 o; o.x = cvt_pk_bf16(y0[0], y0[1]); o.y = cvt_pk_bf16(y0[2], y0[3]); o.z = cvt_pk_bf16(y1[0], y1[1]); o.w = cvt_pk_bf16(y1[2], y1[3]); *(u32x4*)(xout + off + bj * HALF) = o; }
;                 }
.LBB0_448:
	v_add_u32_e32 v188, s15, v197
	v_ashrrev_i32_e32 v189, 31, v188
	v_lshl_add_u64 v[186:187], v[176:177], 1, s[38:39]
	v_lshlrev_b64 v[130:131], 11, v[188:189]
	v_or_b32_e32 v202, 16, v188
	v_lshl_add_u64 v[130:131], v[186:187], 0, v[130:131]
	v_ashrrev_i32_e32 v203, 31, v202
	global_load_dwordx4 v[214:217], v[130:131], off
	global_load_dwordx4 v[154:157], v[130:131], off offset:256
	v_lshlrev_b64 v[130:131], 11, v[202:203]
	v_or_b32_e32 v200, 32, v188
	v_lshl_add_u64 v[130:131], v[186:187], 0, v[130:131]
	v_ashrrev_i32_e32 v201, 31, v200
	global_load_dwordx4 v[150:153], v[130:131], off
	global_load_dwordx4 v[146:149], v[130:131], off offset:256
	v_lshlrev_b64 v[130:131], 11, v[200:201]
	v_or_b32_e32 v190, 48, v188
	v_lshl_add_u64 v[130:131], v[186:187], 0, v[130:131]
	v_ashrrev_i32_e32 v191, 31, v190
	global_load_dwordx4 v[142:145], v[130:131], off
	global_load_dwordx4 v[138:141], v[130:131], off offset:256
	v_lshlrev_b64 v[130:131], 11, v[190:191]
	v_lshl_add_u64 v[130:131], v[186:187], 0, v[130:131]
	global_load_dwordx4 v[134:137], v[130:131], off
	s_nop 0
	global_load_dwordx4 v[130:133], v[130:131], off offset:256
	v_cndmask_b32_e64 v204, 0, 1, s[70:71]
	v_cmp_ne_u32_e64 s[42:43], 1, v204
	v_lshlrev_b64 v[204:205], 10, v[188:189]
	v_lshl_add_u64 v[206:207], v[204:205], 0, v[176:177]
	s_andn2_b64 vcc, exec, s[70:71]
	v_lshl_add_u64 v[206:207], v[206:207], 2, s[46:47]
	s_waitcnt vmcnt(0) lgkmcnt(0)
	v_lshlrev_b32_e32 v232, 16, v214
	v_and_b32_e32 v233, 0xffff0000, v214
	v_lshlrev_b32_e32 v214, 16, v215
	v_and_b32_e32 v215, 0xffff0000, v215
	v_lshlrev_b32_e32 v234, 16, v216
	v_and_b32_e32 v235, 0xffff0000, v216
	v_lshlrev_b32_e32 v216, 16, v217
	v_and_b32_e32 v217, 0xffff0000, v217
	v_pk_fma_f32 v[128:129], v[128:129], v[184:185], v[214:215]
	v_pk_fma_f32 v[126:127], v[126:127], v[182:183], v[232:233]
	v_pk_fma_f32 v[124:125], v[124:125], v[180:181], v[216:217]
	v_pk_fma_f32 v[122:123], v[122:123], v[178:179], v[234:235]
	s_cbranch_vccnz .LBB0_499
	global_store_dwordx4 v[206:207], v[126:129], off
	global_store_dwordx4 v[206:207], v[122:125], off offset:16
	v_lshl_add_u64 v[204:205], v[204:205], 1, v[186:187]
	s_cbranch_execnz .LBB0_451
.LBB0_450:
	v_cvt_pk_bf16_f32 v126, v126, v127
	v_cvt_pk_bf16_f32 v127, v128, v129
	v_cvt_pk_bf16_f32 v128, v122, v123
	v_cvt_pk_bf16_f32 v129, v124, v125
	global_store_dwordx4 v[204:205], v[126:129], off
.LBB0_451:
	v_lshlrev_b32_e32 v122, 16, v154
	v_and_b32_e32 v123, 0xffff0000, v154
	v_lshlrev_b32_e32 v124, 16, v155
	v_and_b32_e32 v125, 0xffff0000, v155
	v_lshlrev_b32_e32 v126, 16, v156
	v_and_b32_e32 v127, 0xffff0000, v156
	v_lshlrev_b32_e32 v128, 16, v157
	v_and_b32_e32 v129, 0xffff0000, v157
	v_pk_fma_f32 v[120:121], v[120:121], v[174:175], v[124:125]
	v_pk_fma_f32 v[118:119], v[118:119], v[172:173], v[122:123]
	v_pk_fma_f32 v[116:117], v[116:117], v[170:171], v[128:129]
	s_and_b64 vcc, exec, s[42:43]
	v_pk_fma_f32 v[114:115], v[114:115], v[168:169], v[126:127]
	s_cbranch_vccnz .LBB0_500
	global_store_dwordx4 v[206:207], v[118:121], off offset:512
	global_store_dwordx4 v[206:207], v[114:117], off offset:528
	s_cbranch_execnz .LBB0_454
.LBB0_453:
	v_cvt_pk_bf16_f32 v118, v118, v119
	v_cvt_pk_bf16_f32 v119, v120, v121
	v_cvt_pk_bf16_f32 v120, v114, v115
	v_cvt_pk_bf16_f32 v121, v116, v117
	global_store_dwordx4 v[204:205], v[118:121], off offset:256
.LBB0_454:
	v_lshlrev_b64 v[114:115], 10, v[202:203]
	v_lshl_add_u64 v[116:117], v[114:115], 0, v[176:177]
	v_lshlrev_b32_e32 v118, 16, v150
	v_and_b32_e32 v119, 0xffff0000, v150
	v_lshlrev_b32_e32 v120, 16, v151
	v_and_b32_e32 v121, 0xffff0000, v151
	v_lshlrev_b32_e32 v122, 16, v152
	v_and_b32_e32 v123, 0xffff0000, v152
	v_lshlrev_b32_e32 v124, 16, v153
	v_and_b32_e32 v125, 0xffff0000, v153
	v_pk_fma_f32 v[112:113], v[112:113], v[184:185], v[120:121]
	v_pk_fma_f32 v[110:111], v[110:111], v[182:183], v[118:119]
	v_pk_fma_f32 v[108:109], v[108:109], v[180:181], v[124:125]
	v_pk_fma_f32 v[106:107], v[106:107], v[178:179], v[122:123]
	s_and_b64 vcc, exec, s[42:43]
	v_lshl_add_u64 v[116:117], v[116:117], 2, s[46:47]
	s_cbranch_vccnz .LBB0_501
	global_store_dwordx4 v[116:117], v[110:113], off
	global_store_dwordx4 v[116:117], v[106:109], off offset:16
	v_lshl_add_u64 v[114:115], v[114:115], 1, v[186:187]
	s_cbranch_execnz .LBB0_457
.LBB0_456:
	v_cvt_pk_bf16_f32 v110, v110, v111
	v_cvt_pk_bf16_f32 v111, v112, v113
	v_cvt_pk_bf16_f32 v112, v106, v107
	v_cvt_pk_bf16_f32 v113, v108, v109
	global_store_dwordx4 v[114:115], v[110:113], off
.LBB0_457:
	v_lshlrev_b32_e32 v106, 16, v146
	v_and_b32_e32 v107, 0xffff0000, v146
	v_lshlrev_b32_e32 v108, 16, v147
	v_and_b32_e32 v109, 0xffff0000, v147
	v_lshlrev_b32_e32 v110, 16, v148
	v_and_b32_e32 v111, 0xffff0000, v148
	v_lshlrev_b32_e32 v112, 16, v149
	v_and_b32_e32 v113, 0xffff0000, v149
	v_pk_fma_f32 v[104:105], v[104:105], v[174:175], v[108:109]
	v_pk_fma_f32 v[102:103], v[102:103], v[172:173], v[106:107]
	v_pk_fma_f32 v[100:101], v[100:101], v[170:171], v[112:113]
	s_and_b64 vcc, exec, s[42:43]
	v_pk_fma_f32 v[98:99], v[98:99], v[168:169], v[110:111]
	s_cbranch_vccnz .LBB0_502
	global_store_dwordx4 v[116:117], v[102:105], off offset:512
	global_store_dwordx4 v[116:117], v[98:101], off offset:528
	s_cbranch_execnz .LBB0_460
.LBB0_459:
	v_cvt_pk_bf16_f32 v102, v102, v103
	v_cvt_pk_bf16_f32 v103, v104, v105
	v_cvt_pk_bf16_f32 v104, v98, v99
	v_cvt_pk_bf16_f32 v105, v100, v101
	global_store_dwordx4 v[114:115], v[102:105], off offset:256
; __device__ __forceinline__ unsigned cvt_pk_bf16(float lo, float hi) { unsigned r; asm volatile("v_cvt_pk_bf16_f32 %0, %1, %2" : "=v"(r) : "v"(lo), "v"(hi)); return r; }
;     __device__ __forceinline__ void operator()(const f32x4 (&acc)[2][2][4][2], const Unit& u, int wr, int wc, int fr, int fq) const {
;     ...
; #pragma unroll
;         for (int ai = 0; ai < 2; ++ai) {
;             u32x4 xb[4][2];
; #pragma unroll
;             for (int m = 0; m < 4; ++m)
; #pragma unroll
;                 for (int bj = 0; bj < 2; ++bj) xb[m][bj] = *(const u32x4*)(xin + (size_t)(rowt + ai * HALF + wr * 64 + m * 16 + fr) * DM + col0 + bj * HALF);
; #pragma unroll
;             for (int m = 0; m < 4; ++m) {
;                 const size_t off = (size_t)(rowt + ai * HALF + wr * 64 + m * 16 + fr) * DM + col0;
; #pragma unroll
;                 for (int bj = 0; bj < 2; ++bj) {
;                     const u32x4 x = xb[m][bj];
;                     const f32x4 x0 = {__builtin_bit_cast(float, x.x << 16), __builtin_bit_cast(float, x.x & 0xffff0000u), __builtin_bit_cast(float, x.y << 16), __builtin_bit_cast(float, x.y & 0xffff0000u)};
;                     const f32x4 x1 = {__builtin_bit_cast(float, x.z << 16), __builtin_bit_cast(float, x.z & 0xffff0000u), __builtin_bit_cast(float, x.w << 16), __builtin_bit_cast(float, x.w & 0xffff0000u)};
;                     const f32x4 y0 = x0 + g[bj][0] * acc[ai][bj][m][0], y1 = x1 + g[bj][1] * acc[ai][bj][m][1];
;                     if (fout) { *(f32x4*)(fout + off + bj * HALF) = y0; *(f32x4*)(fout + off + bj * HALF + 4) = y1; }
;                     else { u32x4 o; o.x = cvt_pk_bf16(y0[0], y0[1]); o.y = cvt_pk_bf16(y0[2], y0[3]); o.z = cvt_pk_bf16(y1[0], y1[1]); o.w = cvt_pk_bf16(y1[2], y1[3]); *(u32x4*)(xout + off + bj * HALF) = o; }
;                 }
.LBB0_460:
	v_lshlrev_b64 v[98:99], 10, v[200:201]
	v_lshl_add_u64 v[100:101], v[98:99], 0, v[176:177]
	v_lshlrev_b32_e32 v102, 16, v142
	v_and_b32_e32 v103, 0xffff0000, v142
	v_lshlrev_b32_e32 v104, 16, v143
	v_and_b32_e32 v105, 0xffff0000, v143
	v_lshlrev_b32_e32 v106, 16, v144
	v_and_b32_e32 v107, 0xffff0000, v144
	v_lshlrev_b32_e32 v108, 16, v145
	v_and_b32_e32 v109, 0xffff0000, v145
	v_pk_fma_f32 v[96:97], v[96:97], v[184:185], v[104:105]
	v_pk_fma_f32 v[94:95], v[94:95], v[182:183], v[102:103]
	v_pk_fma_f32 v[92:93], v[92:93], v[180:181], v[108:109]
	v_pk_fma_f32 v[90:91], v[90:91], v[178:179], v[106:107]
	s_and_b64 vcc, exec, s[42:43]
	v_lshl_add_u64 v[100:101], v[100:101], 2, s[46:47]
	s_cbranch_vccnz .LBB0_503
	global_store_dwordx4 v[100:101], v[94:97], off
	global_store_dwordx4 v[100:101], v[90:93], off offset:16
	v_lshl_add_u64 v[98:99], v[98:99], 1, v[186:187]
	s_cbranch_execnz .LBB0_463
.LBB0_462:
	v_cvt_pk_bf16_f32 v94, v94, v95
	v_cvt_pk_bf16_f32 v95, v96, v97
	v_cvt_pk_bf16_f32 v96, v90, v91
	v_cvt_pk_bf16_f32 v97, v92, v93
	global_store_dwordx4 v[98:99], v[94:97], off
.LBB0_463:
	v_lshlrev_b32_e32 v90, 16, v138
	v_and_b32_e32 v91, 0xffff0000, v138
	v_lshlrev_b32_e32 v92, 16, v139
	v_and_b32_e32 v93, 0xffff0000, v139
	v_lshlrev_b32_e32 v94, 16, v140
	v_and_b32_e32 v95, 0xffff0000, v140
	v_lshlrev_b32_e32 v96, 16, v141
	v_and_b32_e32 v97, 0xffff0000, v141
	v_pk_fma_f32 v[88:89], v[88:89], v[174:175], v[92:93]
	v_pk_fma_f32 v[86:87], v[86:87], v[172:173], v[90:91]
	v_pk_fma_f32 v[84:85], v[84:85], v[170:171], v[96:97]
	s_and_b64 vcc, exec, s[42:43]
	v_pk_fma_f32 v[82:83], v[82:83], v[168:169], v[94:95]
	s_cbranch_vccnz .LBB0_504
	global_store_dwordx4 v[100:101], v[86:89], off offset:512
	global_store_dwordx4 v[100:101], v[82:85], off offset:528
	s_cbranch_execnz .LBB0_466
.LBB0_465:
	v_cvt_pk_bf16_f32 v86, v86, v87
	v_cvt_pk_bf16_f32 v87, v88, v89
	v_cvt_pk_bf16_f32 v88, v82, v83
	v_cvt_pk_bf16_f32 v89, v84, v85
	global_store_dwordx4 v[98:99], v[86:89], off offset:256
.LBB0_466:
	v_lshlrev_b64 v[82:83], 10, v[190:191]
	v_lshl_add_u64 v[84:85], v[82:83], 0, v[176:177]
	v_lshlrev_b32_e32 v86, 16, v134
	v_and_b32_e32 v87, 0xffff0000, v134
	v_lshlrev_b32_e32 v88, 16, v135
	v_and_b32_e32 v89, 0xffff0000, v135
	v_lshlrev_b32_e32 v90, 16, v136
	v_and_b32_e32 v91, 0xffff0000, v136
	v_lshlrev_b32_e32 v92, 16, v137
	v_and_b32_e32 v93, 0xffff0000, v137
	v_pk_fma_f32 v[80:81], v[80:81], v[184:185], v[88:89]
	v_pk_fma_f32 v[78:79], v[78:79], v[182:183], v[86:87]
	v_pk_fma_f32 v[76:77], v[76:77], v[180:181], v[92:93]
	v_pk_fma_f32 v[74:75], v[74:75], v[178:179], v[90:91]
	s_and_b64 vcc, exec, s[42:43]
	v_lshl_add_u64 v[84:85], v[84:85], 2, s[46:47]
	s_cbranch_vccnz .LBB0_505
	global_store_dwordx4 v[84:85], v[78:81], off
	global_store_dwordx4 v[84:85], v[74:77], off offset:16
	v_lshl_add_u64 v[82:83], v[82:83], 1, v[186:187]
	s_cbranch_execnz .LBB0_469
.LBB0_468:
	v_cvt_pk_bf16_f32 v78, v78, v79
	v_cvt_pk_bf16_f32 v79, v80, v81
	v_cvt_pk_bf16_f32 v80, v74, v75
	v_cvt_pk_bf16_f32 v81, v76, v77
	global_store_dwordx4 v[82:83], v[78:81], off
.LBB0_469:
	v_lshlrev_b32_e32 v74, 16, v130
	v_and_b32_e32 v75, 0xffff0000, v130
	v_lshlrev_b32_e32 v76, 16, v131
	v_and_b32_e32 v77, 0xffff0000, v131
	v_lshlrev_b32_e32 v78, 16, v132
	v_and_b32_e32 v79, 0xffff0000, v132
	v_lshlrev_b32_e32 v80, 16, v133
	v_and_b32_e32 v81, 0xffff0000, v133
	v_pk_fma_f32 v[72:73], v[72:73], v[174:175], v[76:77]
	v_pk_fma_f32 v[70:71], v[70:71], v[172:173], v[74:75]
	v_pk_fma_f32 v[68:69], v[68:69], v[170:171], v[80:81]
	s_and_b64 vcc, exec, s[42:43]
	v_pk_fma_f32 v[66:67], v[66:67], v[168:169], v[78:79]
	s_cbranch_vccnz .LBB0_506
	global_store_dwordx4 v[84:85], v[70:73], off offset:512
	global_store_dwordx4 v[84:85], v[66:69], off offset:528
	s_cbranch_execnz .LBB0_472
.LBB0_471:
	v_cvt_pk_bf16_f32 v70, v70, v71
	v_cvt_pk_bf16_f32 v71, v72, v73
	v_cvt_pk_bf16_f32 v72, v66, v67
	v_cvt_pk_bf16_f32 v73, v68, v69
	global_store_dwordx4 v[82:83], v[70:73], off offset:256
.LBB0_472:
	v_add_u32_e32 v100, 0x80, v188
	v_ashrrev_i32_e32 v101, 31, v100
	v_lshlrev_b64 v[66:67], 11, v[100:101]
	v_add_u32_e32 v98, 0x90, v188
	v_lshl_add_u64 v[66:67], v[186:187], 0, v[66:67]
	v_ashrrev_i32_e32 v99, 31, v98
	global_load_dwordx4 v[102:105], v[66:67], off
	global_load_dwordx4 v[90:93], v[66:67], off offset:256
	v_lshlrev_b64 v[66:67], 11, v[98:99]
	v_add_u32_e32 v96, 0xa0, v188
	v_lshl_add_u64 v[66:67], v[186:187], 0, v[66:67]
	v_ashrrev_i32_e32 v97, 31, v96
	global_load_dwordx4 v[86:89], v[66:67], off
	global_load_dwordx4 v[82:85], v[66:67], off offset:256
	v_lshlrev_b64 v[66:67], 11, v[96:97]
	v_add_u32_e32 v94, 0xb0, v188
	v_lshl_add_u64 v[66:67], v[186:187], 0, v[66:67]
	v_ashrrev_i32_e32 v95, 31, v94
	global_load_dwordx4 v[78:81], v[66:67], off
	global_load_dwordx4 v[74:77], v[66:67], off offset:256
	v_lshlrev_b64 v[66:67], 11, v[94:95]
	v_lshl_add_u64 v[66:67], v[186:187], 0, v[66:67]
	global_load_dwordx4 v[70:73], v[66:67], off
	s_nop 0
	global_load_dwordx4 v[66:69], v[66:67], off offset:256
	v_lshlrev_b64 v[100:101], 10, v[100:101]
	v_lshl_add_u64 v[106:107], v[100:101], 0, v[176:177]
	s_and_b64 vcc, exec, s[42:43]
	s_waitcnt vmcnt(0) lgkmcnt(0)
	v_lshlrev_b32_e32 v108, 16, v102
	v_and_b32_e32 v109, 0xffff0000, v102
	v_lshlrev_b32_e32 v102, 16, v103
	v_and_b32_e32 v103, 0xffff0000, v103
	v_lshlrev_b32_e32 v110, 16, v104
	v_and_b32_e32 v111, 0xffff0000, v104
	v_lshlrev_b32_e32 v104, 16, v105
	v_and_b32_e32 v105, 0xffff0000, v105
	v_pk_fma_f32 v[64:65], v[64:65], v[184:185], v[102:103]
	v_pk_fma_f32 v[62:63], v[62:63], v[182:183], v[108:109]
	v_pk_fma_f32 v[60:61], v[60:61], v[180:181], v[104:105]
	v_pk_fma_f32 v[58:59], v[58:59], v[178:179], v[110:111]
	v_lshl_add_u64 v[102:103], v[106:107], 2, s[46:47]
	s_cbranch_vccnz .LBB0_507
	global_store_dwordx4 v[102:103], v[62:65], off
	global_store_dwordx4 v[102:103], v[58:61], off offset:16
	v_lshl_add_u64 v[100:101], v[100:101], 1, v[186:187]
	s_cbranch_execnz .LBB0_475
; __device__ __forceinline__ unsigned cvt_pk_bf16(float lo, float hi) { unsigned r; asm volatile("v_cvt_pk_bf16_f32 %0, %1, %2" : "=v"(r) : "v"(lo), "v"(hi)); return r; }
;     __device__ __forceinline__ void operator()(const f32x4 (&acc)[2][2][4][2], const Unit& u, int wr, int wc, int fr, int fq) const {
;     ...
;             for (int m = 0; m < 4; ++m) {
;                 const size_t off = (size_t)(rowt + ai * HALF + wr * 64 + m * 16 + fr) * DM + col0;
; #pragma unroll
;                 for (int bj = 0; bj < 2; ++bj) {
;                     const u32x4 x = xb[m][bj];
;                     const f32x4 x0 = {__builtin_bit_cast(float, x.x << 16), __builtin_bit_cast(float, x.x & 0xffff0000u), __builtin_bit_cast(float, x.y << 16), __builtin_bit_cast(float, x.y & 0xffff0000u)};
;                     const f32x4 x1 = {__builtin_bit_cast(float, x.z << 16), __builtin_bit_cast(float, x.z & 0xffff0000u), __builtin_bit_cast(float, x.w << 16), __builtin_bit_cast(float, x.w & 0xffff0000u)};
;                     const f32x4 y0 = x0 + g[bj][0] * acc[ai][bj][m][0], y1 = x1 + g[bj][1] * acc[ai][bj][m][1];
;                     if (fout) { *(f32x4*)(fout + off + bj * HALF) = y0; *(f32x4*)(fout + off + bj * HALF + 4) = y1; }
;                     else { u32x4 o; o.x = cvt_pk_bf16(y0[0], y0[1]); o.y = cvt_pk_bf16(y0[2], y0[3]); o.z = cvt_pk_bf16(y1[0], y1[1]); o.w = cvt_pk_bf16(y1[2], y1[3]); *(u32x4*)(xout + off + bj * HALF) = o; }
;                 }
.LBB0_474:
	v_cvt_pk_bf16_f32 v62, v62, v63
	v_cvt_pk_bf16_f32 v63, v64, v65
	v_cvt_pk_bf16_f32 v64, v58, v59
	v_cvt_pk_bf16_f32 v65, v60, v61
	global_store_dwordx4 v[100:101], v[62:65], off
.LBB0_475:
	v_lshlrev_b32_e32 v58, 16, v90
	v_and_b32_e32 v59, 0xffff0000, v90
	v_lshlrev_b32_e32 v60, 16, v91
	v_and_b32_e32 v61, 0xffff0000, v91
	v_lshlrev_b32_e32 v62, 16, v92
	v_and_b32_e32 v63, 0xffff0000, v92
	v_lshlrev_b32_e32 v64, 16, v93
	v_and_b32_e32 v65, 0xffff0000, v93
	v_pk_fma_f32 v[56:57], v[56:57], v[174:175], v[60:61]
	v_pk_fma_f32 v[54:55], v[54:55], v[172:173], v[58:59]
	v_pk_fma_f32 v[52:53], v[52:53], v[170:171], v[64:65]
	s_and_b64 vcc, exec, s[42:43]
	v_pk_fma_f32 v[50:51], v[50:51], v[168:169], v[62:63]
	s_cbranch_vccnz .LBB0_508
	global_store_dwordx4 v[102:103], v[54:57], off offset:512
	global_store_dwordx4 v[102:103], v[50:53], off offset:528
	s_cbranch_execnz .LBB0_478
.LBB0_477:
	v_cvt_pk_bf16_f32 v54, v54, v55
	v_cvt_pk_bf16_f32 v55, v56, v57
	v_cvt_pk_bf16_f32 v56, v50, v51
	v_cvt_pk_bf16_f32 v57, v52, v53
	global_store_dwordx4 v[100:101], v[54:57], off offset:256
.LBB0_478:
	v_lshlrev_b64 v[50:51], 10, v[98:99]
	v_lshl_add_u64 v[52:53], v[50:51], 0, v[176:177]
	v_lshlrev_b32_e32 v54, 16, v86
	v_and_b32_e32 v55, 0xffff0000, v86
	v_lshlrev_b32_e32 v56, 16, v87
	v_and_b32_e32 v57, 0xffff0000, v87
	v_lshlrev_b32_e32 v58, 16, v88
	v_and_b32_e32 v59, 0xffff0000, v88
	v_lshlrev_b32_e32 v60, 16, v89
	v_and_b32_e32 v61, 0xffff0000, v89
	v_pk_fma_f32 v[48:49], v[48:49], v[184:185], v[56:57]
	v_pk_fma_f32 v[46:47], v[46:47], v[182:183], v[54:55]
	v_pk_fma_f32 v[44:45], v[44:45], v[180:181], v[60:61]
	v_pk_fma_f32 v[42:43], v[42:43], v[178:179], v[58:59]
	s_and_b64 vcc, exec, s[42:43]
	v_lshl_add_u64 v[52:53], v[52:53], 2, s[46:47]
	s_cbranch_vccnz .LBB0_509
	global_store_dwordx4 v[52:53], v[46:49], off
	global_store_dwordx4 v[52:53], v[42:45], off offset:16
	v_lshl_add_u64 v[50:51], v[50:51], 1, v[186:187]
	s_cbranch_execnz .LBB0_481
.LBB0_480:
	v_cvt_pk_bf16_f32 v46, v46, v47
	v_cvt_pk_bf16_f32 v47, v48, v49
	v_cvt_pk_bf16_f32 v48, v42, v43
	v_cvt_pk_bf16_f32 v49, v44, v45
	global_store_dwordx4 v[50:51], v[46:49], off
.LBB0_481:
	v_lshlrev_b32_e32 v42, 16, v82
	v_and_b32_e32 v43, 0xffff0000, v82
	v_lshlrev_b32_e32 v44, 16, v83
	v_and_b32_e32 v45, 0xffff0000, v83
	v_lshlrev_b32_e32 v46, 16, v84
	v_and_b32_e32 v47, 0xffff0000, v84
	v_lshlrev_b32_e32 v48, 16, v85
	v_and_b32_e32 v49, 0xffff0000, v85
	v_pk_fma_f32 v[40:41], v[40:41], v[174:175], v[44:45]
	v_pk_fma_f32 v[38:39], v[38:39], v[172:173], v[42:43]
	v_pk_fma_f32 v[36:37], v[36:37], v[170:171], v[48:49]
	s_and_b64 vcc, exec, s[42:43]
	v_pk_fma_f32 v[34:35], v[34:35], v[168:169], v[46:47]
	s_cbranch_vccnz .LBB0_510
	global_store_dwordx4 v[52:53], v[38:41], off offset:512
	global_store_dwordx4 v[52:53], v[34:37], off offset:528
	s_cbranch_execnz .LBB0_484
.LBB0_483:
	v_cvt_pk_bf16_f32 v38, v38, v39
	v_cvt_pk_bf16_f32 v39, v40, v41
	v_cvt_pk_bf16_f32 v40, v34, v35
	v_cvt_pk_bf16_f32 v41, v36, v37
	global_store_dwordx4 v[50:51], v[38:41], off offset:256
.LBB0_484:
	v_lshlrev_b64 v[34:35], 10, v[96:97]
	v_lshl_add_u64 v[36:37], v[34:35], 0, v[176:177]
	v_lshlrev_b32_e32 v38, 16, v78
	v_and_b32_e32 v39, 0xffff0000, v78
	v_lshlrev_b32_e32 v40, 16, v79
	v_and_b32_e32 v41, 0xffff0000, v79
	v_lshlrev_b32_e32 v42, 16, v80
	v_and_b32_e32 v43, 0xffff0000, v80
	v_lshlrev_b32_e32 v44, 16, v81
	v_and_b32_e32 v45, 0xffff0000, v81
	v_pk_fma_f32 v[32:33], v[32:33], v[184:185], v[40:41]
	v_pk_fma_f32 v[30:31], v[30:31], v[182:183], v[38:39]
	v_pk_fma_f32 v[28:29], v[28:29], v[180:181], v[44:45]
	v_pk_fma_f32 v[26:27], v[26:27], v[178:179], v[42:43]
	s_and_b64 vcc, exec, s[42:43]
	v_lshl_add_u64 v[36:37], v[36:37], 2, s[46:47]
	s_cbranch_vccnz .LBB0_511
	global_store_dwordx4 v[36:37], v[30:33], off
	global_store_dwordx4 v[36:37], v[26:29], off offset:16
	v_lshl_add_u64 v[34:35], v[34:35], 1, v[186:187]
	s_cbranch_execnz .LBB0_487
.LBB0_486:
	v_cvt_pk_bf16_f32 v30, v30, v31
	v_cvt_pk_bf16_f32 v31, v32, v33
	v_cvt_pk_bf16_f32 v32, v26, v27
	v_cvt_pk_bf16_f32 v33, v28, v29
	global_store_dwordx4 v[34:35], v[30:33], off
.LBB0_487:
	v_lshlrev_b32_e32 v26, 16, v74
	v_and_b32_e32 v27, 0xffff0000, v74
	v_lshlrev_b32_e32 v28, 16, v75
	v_and_b32_e32 v29, 0xffff0000, v75
	v_lshlrev_b32_e32 v30, 16, v76
	v_and_b32_e32 v31, 0xffff0000, v76
	v_lshlrev_b32_e32 v32, 16, v77
	v_and_b32_e32 v33, 0xffff0000, v77
	v_pk_fma_f32 v[24:25], v[24:25], v[174:175], v[28:29]
	v_pk_fma_f32 v[22:23], v[22:23], v[172:173], v[26:27]
	v_pk_fma_f32 v[20:21], v[20:21], v[170:171], v[32:33]
	s_and_b64 vcc, exec, s[42:43]
	v_pk_fma_f32 v[18:19], v[18:19], v[168:169], v[30:31]
	s_cbranch_vccnz .LBB0_512
	global_store_dwordx4 v[36:37], v[22:25], off offset:512
	global_store_dwordx4 v[36:37], v[18:21], off offset:528
	s_cbranch_execnz .LBB0_490
.LBB0_489:
	v_cvt_pk_bf16_f32 v22, v22, v23
	v_cvt_pk_bf16_f32 v23, v24, v25
	v_cvt_pk_bf16_f32 v24, v18, v19
	v_cvt_pk_bf16_f32 v25, v20, v21
	global_store_dwordx4 v[34:35], v[22:25], off offset:256
.LBB0_490:
	v_lshlrev_b64 v[18:19], 10, v[94:95]
	v_lshl_add_u64 v[20:21], v[18:19], 0, v[176:177]
	v_lshlrev_b32_e32 v22, 16, v70
	v_and_b32_e32 v23, 0xffff0000, v70
	v_lshlrev_b32_e32 v24, 16, v71
	v_and_b32_e32 v25, 0xffff0000, v71
	v_lshlrev_b32_e32 v26, 16, v72
	v_and_b32_e32 v27, 0xffff0000, v72
	v_lshlrev_b32_e32 v28, 16, v73
	v_and_b32_e32 v29, 0xffff0000, v73
	v_pk_fma_f32 v[16:17], v[16:17], v[184:185], v[24:25]
	v_pk_fma_f32 v[14:15], v[14:15], v[182:183], v[22:23]
	v_pk_fma_f32 v[12:13], v[12:13], v[180:181], v[28:29]
	v_pk_fma_f32 v[10:11], v[10:11], v[178:179], v[26:27]
	s_and_b64 vcc, exec, s[42:43]
	v_lshl_add_u64 v[20:21], v[20:21], 2, s[46:47]
	s_cbranch_vccnz .LBB0_513
	global_store_dwordx4 v[20:21], v[14:17], off
	global_store_dwordx4 v[20:21], v[10:13], off offset:16
	v_lshl_add_u64 v[18:19], v[18:19], 1, v[186:187]
	s_cbranch_execnz .LBB0_493
.LBB0_492:
	v_cvt_pk_bf16_f32 v14, v14, v15
	v_cvt_pk_bf16_f32 v15, v16, v17
	v_cvt_pk_bf16_f32 v16, v10, v11
	v_cvt_pk_bf16_f32 v17, v12, v13
	global_store_dwordx4 v[18:19], v[14:17], off
.LBB0_493:
	v_lshlrev_b32_e32 v10, 16, v66
	v_and_b32_e32 v11, 0xffff0000, v66
	v_lshlrev_b32_e32 v12, 16, v67
	v_and_b32_e32 v13, 0xffff0000, v67
	v_lshlrev_b32_e32 v14, 16, v68
	v_and_b32_e32 v15, 0xffff0000, v68
	v_lshlrev_b32_e32 v16, 16, v69
	v_and_b32_e32 v17, 0xffff0000, v69
	v_pk_fma_f32 v[8:9], v[8:9], v[174:175], v[12:13]
	v_pk_fma_f32 v[6:7], v[6:7], v[172:173], v[10:11]
	v_pk_fma_f32 v[4:5], v[4:5], v[170:171], v[16:17]
	s_and_b64 vcc, exec, s[42:43]
	v_pk_fma_f32 v[2:3], v[2:3], v[168:169], v[14:15]
	s_cbranch_vccnz .LBB0_514
	global_store_dwordx4 v[20:21], v[6:9], off offset:512
	global_store_dwordx4 v[20:21], v[2:5], off offset:528
	s_cbranch_execnz .LBB0_496
.LBB0_495:
	v_cvt_pk_bf16_f32 v6, v6, v7
	v_cvt_pk_bf16_f32 v7, v8, v9
	v_cvt_pk_bf16_f32 v8, v2, v3
	v_cvt_pk_bf16_f32 v9, v4, v5
	global_store_dwordx4 v[18:19], v[6:9], off offset:256

; __device__ __forceinline__ unsigned cvt_pk_bf16(float lo, float hi) { unsigned r; asm volatile("v_cvt_pk_bf16_f32 %0, %1, %2" : "=v"(r) : "v"(lo), "v"(hi)); return r; }
; __device__ __forceinline__ float silu_f(float g) { return g * __builtin_amdgcn_rcpf(1.0f + __expf(-g)); }
;     __device__ __forceinline__ void operator()(const f32x4 (&acc)[2][2][4][2], const Unit& u, int wr, int wc, int fr, int fq) const {
;         const int row0 = u.pm * BM + wr * 64 + fr, col0 = u.pn * HALF + wc * 32 + 8 * fq;
; #pragma unroll
;         for (int ai = 0; ai < 2; ++ai)
; #pragma unroll
;             for (int m = 0; m < 4; ++m) {
;                 bf16_t* rowp = O + (size_t)(row0 + ai * HALF + m * 16) * DFF + col0;
;                 const f32x4 g0 = acc[ai][0][m][0], g1 = acc[ai][0][m][1], u0 = acc[ai][1][m][0], u1 = acc[ai][1][m][1];
;                 u32x4 w;
;                 w.x = cvt_pk_bf16(silu_f(g0[0]) * u0[0], silu_f(g0[1]) * u0[1]);
;                 w.y = cvt_pk_bf16(silu_f(g0[2]) * u0[2], silu_f(g0[3]) * u0[3]);
;                 w.z = cvt_pk_bf16(silu_f(g1[0]) * u1[0], silu_f(g1[1]) * u1[1]);
;                 w.w = cvt_pk_bf16(silu_f(g1[2]) * u1[2], silu_f(g1[3]) * u1[3]);
;                 *(u32x4*)rowp = w;
;             }
.LBB0_529:
	v_lshl_or_b32 v142, s53, 7, v146
	v_lshl_add_u32 v148, s52, 8, v144
	v_ashrrev_i32_e32 v143, 31, v142
	v_mov_b64_e32 v[140:141], s[38:39]
	v_lshlrev_b64 v[142:143], 1, v[142:143]
	s_andn2_b64 vcc, exec, s[40:41]
	v_mov_b32_e32 v160, 0xbfb8aa3b
	v_mad_i64_i32 v[150:151], s[52:53], v148, s79, v[140:141]
	v_pk_mul_f32 v[152:153], v[126:127], v[160:161] op_sel_hi:[1,0]
	v_pk_mul_f32 v[154:155], v[128:129], v[160:161] op_sel_hi:[1,0]
	v_pk_mul_f32 v[156:157], v[118:119], v[160:161] op_sel_hi:[1,0]
	v_pk_mul_f32 v[158:159], v[120:121], v[160:161] op_sel_hi:[1,0]
	v_lshl_add_u64 v[150:151], v[150:151], 0, v[142:143]
	v_exp_f32_e32 v152, v152
	v_exp_f32_e32 v153, v153
	v_exp_f32_e32 v154, v154
	v_exp_f32_e32 v155, v155
	v_exp_f32_e32 v156, v156
	v_exp_f32_e32 v157, v157
	v_exp_f32_e32 v158, v158
	v_exp_f32_e32 v159, v159
	v_pk_add_f32 v[152:153], v[152:153], 1.0 op_sel_hi:[1,0]
	v_pk_add_f32 v[154:155], v[154:155], 1.0 op_sel_hi:[1,0]
	v_pk_add_f32 v[156:157], v[156:157], 1.0 op_sel_hi:[1,0]
	v_pk_add_f32 v[158:159], v[158:159], 1.0 op_sel_hi:[1,0]
	v_rcp_f32_e32 v152, v152
	v_rcp_f32_e32 v153, v153
	v_rcp_f32_e32 v154, v154
	v_rcp_f32_e32 v155, v155
	v_rcp_f32_e32 v156, v156
	v_rcp_f32_e32 v157, v157
	v_rcp_f32_e32 v158, v158
	v_rcp_f32_e32 v159, v159
	v_pk_mul_f32 v[152:153], v[126:127], v[152:153]
	v_pk_mul_f32 v[154:155], v[128:129], v[154:155]
	v_pk_mul_f32 v[156:157], v[118:119], v[156:157]
	v_pk_mul_f32 v[158:159], v[120:121], v[158:159]
	v_pk_mul_f32 v[152:153], v[122:123], v[152:153]
	v_pk_mul_f32 v[154:155], v[124:125], v[154:155]
	v_pk_mul_f32 v[156:157], v[114:115], v[156:157]
	v_pk_mul_f32 v[158:159], v[116:117], v[158:159]
	v_cvt_pk_bf16_f32 v122, v152, v153
	v_cvt_pk_bf16_f32 v123, v154, v155
	v_cvt_pk_bf16_f32 v124, v156, v157
	v_cvt_pk_bf16_f32 v125, v158, v159
	global_store_dwordx4 v[150:151], v[122:125], off
	v_or_b32_e32 v149, 16, v148
	v_mad_i64_i32 v[162:163], s[52:53], v149, s79, v[140:141]
	v_pk_mul_f32 v[152:153], v[110:111], v[160:161] op_sel_hi:[1,0]
	v_pk_mul_f32 v[154:155], v[112:113], v[160:161] op_sel_hi:[1,0]
	v_pk_mul_f32 v[156:157], v[102:103], v[160:161] op_sel_hi:[1,0]
	v_pk_mul_f32 v[158:159], v[104:105], v[160:161] op_sel_hi:[1,0]
	v_lshl_add_u64 v[162:163], v[162:163], 0, v[142:143]
	v_exp_f32_e32 v152, v152
	v_exp_f32_e32 v153, v153
	v_exp_f32_e32 v154, v154
	v_exp_f32_e32 v155, v155
	v_exp_f32_e32 v156, v156
	v_exp_f32_e32 v157, v157
	v_exp_f32_e32 v158, v158
	v_exp_f32_e32 v159, v159
	v_pk_add_f32 v[152:153], v[152:153], 1.0 op_sel_hi:[1,0]
	v_pk_add_f32 v[154:155], v[154:155], 1.0 op_sel_hi:[1,0]
	v_pk_add_f32 v[156:157], v[156:157], 1.0 op_sel_hi:[1,0]
	v_pk_add_f32 v[158:159], v[158:159], 1.0 op_sel_hi:[1,0]
	v_rcp_f32_e32 v152, v152
	v_rcp_f32_e32 v153, v153
	v_rcp_f32_e32 v154, v154
	v_rcp_f32_e32 v155, v155
	v_rcp_f32_e32 v156, v156
	v_rcp_f32_e32 v157, v157
	v_rcp_f32_e32 v158, v158
	v_rcp_f32_e32 v159, v159
	v_pk_mul_f32 v[152:153], v[110:111], v[152:153]
	v_pk_mul_f32 v[154:155], v[112:113], v[154:155]
	v_pk_mul_f32 v[156:157], v[102:103], v[156:157]
	v_pk_mul_f32 v[158:159], v[104:105], v[158:159]
	v_pk_mul_f32 v[152:153], v[106:107], v[152:153]
	v_pk_mul_f32 v[154:155], v[108:109], v[154:155]
	v_pk_mul_f32 v[156:157], v[98:99], v[156:157]
	v_pk_mul_f32 v[158:159], v[100:101], v[158:159]
	v_cvt_pk_bf16_f32 v106, v152, v153
	v_cvt_pk_bf16_f32 v107, v154, v155
	v_cvt_pk_bf16_f32 v108, v156, v157
	v_cvt_pk_bf16_f32 v109, v158, v159
	global_store_dwordx4 v[162:163], v[106:109], off
	v_or_b32_e32 v149, 32, v148
	v_mad_i64_i32 v[150:151], s[52:53], v149, s79, v[140:141]
	v_pk_mul_f32 v[152:153], v[94:95], v[160:161] op_sel_hi:[1,0]
	v_pk_mul_f32 v[154:155], v[96:97], v[160:161] op_sel_hi:[1,0]
	v_pk_mul_f32 v[156:157], v[86:87], v[160:161] op_sel_hi:[1,0]
	v_pk_mul_f32 v[158:159], v[88:89], v[160:161] op_sel_hi:[1,0]
	v_lshl_add_u64 v[150:151], v[150:151], 0, v[142:143]
	v_exp_f32_e32 v152, v152
	v_exp_f32_e32 v153, v153
	v_exp_f32_e32 v154, v154
	v_exp_f32_e32 v155, v155
	v_exp_f32_e32 v156, v156
	v_exp_f32_e32 v157, v157
	v_exp_f32_e32 v158, v158
	v_exp_f32_e32 v159, v159
	v_pk_add_f32 v[152:153], v[152:153], 1.0 op_sel_hi:[1,0]
	v_pk_add_f32 v[154:155], v[154:155], 1.0 op_sel_hi:[1,0]
	v_pk_add_f32 v[156:157], v[156:157], 1.0 op_sel_hi:[1,0]
	v_pk_add_f32 v[158:159], v[158:159], 1.0 op_sel_hi:[1,0]
	v_rcp_f32_e32 v152, v152
	v_rcp_f32_e32 v153, v153
	v_rcp_f32_e32 v154, v154
	v_rcp_f32_e32 v155, v155
	v_rcp_f32_e32 v156, v156
	v_rcp_f32_e32 v157, v157
	v_rcp_f32_e32 v158, v158
	v_rcp_f32_e32 v159, v159
	v_pk_mul_f32 v[152:153], v[94:95], v[152:153]
	v_pk_mul_f32 v[154:155], v[96:97], v[154:155]
	v_pk_mul_f32 v[156:157], v[86:87], v[156:157]
	v_pk_mul_f32 v[158:159], v[88:89], v[158:159]
	v_pk_mul_f32 v[152:153], v[90:91], v[152:153]
	v_pk_mul_f32 v[154:155], v[92:93], v[154:155]
	v_pk_mul_f32 v[156:157], v[82:83], v[156:157]
	v_pk_mul_f32 v[158:159], v[84:85], v[158:159]
	v_cvt_pk_bf16_f32 v90, v152, v153
	v_cvt_pk_bf16_f32 v91, v154, v155
	v_cvt_pk_bf16_f32 v92, v156, v157
	v_cvt_pk_bf16_f32 v93, v158, v159
	global_store_dwordx4 v[150:151], v[90:93], off
	v_or_b32_e32 v149, 48, v148
	v_mad_i64_i32 v[162:163], s[52:53], v149, s79, v[140:141]
	v_pk_mul_f32 v[152:153], v[78:79], v[160:161] op_sel_hi:[1,0]
	v_pk_mul_f32 v[154:155], v[80:81], v[160:161] op_sel_hi:[1,0]
	v_pk_mul_f32 v[156:157], v[70:71], v[160:161] op_sel_hi:[1,0]
	v_pk_mul_f32 v[158:159], v[72:73], v[160:161] op_sel_hi:[1,0]
	v_lshl_add_u64 v[162:163], v[162:163], 0, v[142:143]
	v_exp_f32_e32 v152, v152
	v_exp_f32_e32 v153, v153
	v_exp_f32_e32 v154, v154
	v_exp_f32_e32 v155, v155
	v_exp_f32_e32 v156, v156
; __device__ __forceinline__ unsigned cvt_pk_bf16(float lo, float hi) { unsigned r; asm volatile("v_cvt_pk_bf16_f32 %0, %1, %2" : "=v"(r) : "v"(lo), "v"(hi)); return r; }
; __device__ __forceinline__ float silu_f(float g) { return g * __builtin_amdgcn_rcpf(1.0f + __expf(-g)); }
;     __device__ __forceinline__ void operator()(const f32x4 (&acc)[2][2][4][2], const Unit& u, int wr, int wc, int fr, int fq) const {
;     ...
;             for (int m = 0; m < 4; ++m) {
;                 bf16_t* rowp = O + (size_t)(row0 + ai * HALF + m * 16) * DFF + col0;
;                 const f32x4 g0 = acc[ai][0][m][0], g1 = acc[ai][0][m][1], u0 = acc[ai][1][m][0], u1 = acc[ai][1][m][1];
;                 u32x4 w;
;                 w.x = cvt_pk_bf16(silu_f(g0[0]) * u0[0], silu_f(g0[1]) * u0[1]);
;                 w.y = cvt_pk_bf16(silu_f(g0[2]) * u0[2], silu_f(g0[3]) * u0[3]);
;                 w.z = cvt_pk_bf16(silu_f(g1[0]) * u1[0], silu_f(g1[1]) * u1[1]);
;                 w.w = cvt_pk_bf16(silu_f(g1[2]) * u1[2], silu_f(g1[3]) * u1[3]);
;                 *(u32x4*)rowp = w;
;             }
	v_exp_f32_e32 v157, v157
	v_exp_f32_e32 v158, v158
	v_exp_f32_e32 v159, v159
	v_pk_add_f32 v[152:153], v[152:153], 1.0 op_sel_hi:[1,0]
	v_pk_add_f32 v[154:155], v[154:155], 1.0 op_sel_hi:[1,0]
	v_pk_add_f32 v[156:157], v[156:157], 1.0 op_sel_hi:[1,0]
	v_pk_add_f32 v[158:159], v[158:159], 1.0 op_sel_hi:[1,0]
	v_rcp_f32_e32 v152, v152
	v_rcp_f32_e32 v153, v153
	v_rcp_f32_e32 v154, v154
	v_rcp_f32_e32 v155, v155
	v_rcp_f32_e32 v156, v156
	v_rcp_f32_e32 v157, v157
	v_rcp_f32_e32 v158, v158
	v_rcp_f32_e32 v159, v159
	v_pk_mul_f32 v[152:153], v[78:79], v[152:153]
	v_pk_mul_f32 v[154:155], v[80:81], v[154:155]
	v_pk_mul_f32 v[156:157], v[70:71], v[156:157]
	v_pk_mul_f32 v[158:159], v[72:73], v[158:159]
	v_pk_mul_f32 v[152:153], v[74:75], v[152:153]
	v_pk_mul_f32 v[154:155], v[76:77], v[154:155]
	v_pk_mul_f32 v[156:157], v[66:67], v[156:157]
	v_pk_mul_f32 v[158:159], v[68:69], v[158:159]
	v_cvt_pk_bf16_f32 v74, v152, v153
	v_cvt_pk_bf16_f32 v75, v154, v155
	v_cvt_pk_bf16_f32 v76, v156, v157
	v_cvt_pk_bf16_f32 v77, v158, v159
	global_store_dwordx4 v[162:163], v[74:77], off
	v_add_u32_e32 v149, 0x80, v148
	v_mad_i64_i32 v[150:151], s[52:53], v149, s79, v[140:141]
	v_pk_mul_f32 v[152:153], v[62:63], v[160:161] op_sel_hi:[1,0]
	v_pk_mul_f32 v[154:155], v[64:65], v[160:161] op_sel_hi:[1,0]
	v_pk_mul_f32 v[156:157], v[54:55], v[160:161] op_sel_hi:[1,0]
	v_pk_mul_f32 v[158:159], v[56:57], v[160:161] op_sel_hi:[1,0]
	v_lshl_add_u64 v[150:151], v[150:151], 0, v[142:143]
	v_exp_f32_e32 v152, v152
	v_exp_f32_e32 v153, v153
	v_exp_f32_e32 v154, v154
	v_exp_f32_e32 v155, v155
	v_exp_f32_e32 v156, v156
	v_exp_f32_e32 v157, v157
	v_exp_f32_e32 v158, v158
	v_exp_f32_e32 v159, v159
	v_pk_add_f32 v[152:153], v[152:153], 1.0 op_sel_hi:[1,0]
	v_pk_add_f32 v[154:155], v[154:155], 1.0 op_sel_hi:[1,0]
	v_pk_add_f32 v[156:157], v[156:157], 1.0 op_sel_hi:[1,0]
	v_pk_add_f32 v[158:159], v[158:159], 1.0 op_sel_hi:[1,0]
	v_rcp_f32_e32 v152, v152
	v_rcp_f32_e32 v153, v153
	v_rcp_f32_e32 v154, v154
	v_rcp_f32_e32 v155, v155
	v_rcp_f32_e32 v156, v156
	v_rcp_f32_e32 v157, v157
	v_rcp_f32_e32 v158, v158
	v_rcp_f32_e32 v159, v159
	v_pk_mul_f32 v[152:153], v[62:63], v[152:153]
	v_pk_mul_f32 v[154:155], v[64:65], v[154:155]
	v_pk_mul_f32 v[156:157], v[54:55], v[156:157]
	v_pk_mul_f32 v[158:159], v[56:57], v[158:159]
	v_pk_mul_f32 v[152:153], v[58:59], v[152:153]
	v_pk_mul_f32 v[154:155], v[60:61], v[154:155]
	v_pk_mul_f32 v[156:157], v[50:51], v[156:157]
	v_pk_mul_f32 v[158:159], v[52:53], v[158:159]
	v_cvt_pk_bf16_f32 v58, v152, v153
	v_cvt_pk_bf16_f32 v59, v154, v155
	v_cvt_pk_bf16_f32 v60, v156, v157
	v_cvt_pk_bf16_f32 v61, v158, v159
	global_store_dwordx4 v[150:151], v[58:61], off
	v_add_u32_e32 v149, 0x90, v148
	v_mad_i64_i32 v[162:163], s[52:53], v149, s79, v[140:141]
	v_pk_mul_f32 v[152:153], v[46:47], v[160:161] op_sel_hi:[1,0]
	v_pk_mul_f32 v[154:155], v[48:49], v[160:161] op_sel_hi:[1,0]
	v_pk_mul_f32 v[156:157], v[38:39], v[160:161] op_sel_hi:[1,0]
	v_pk_mul_f32 v[158:159], v[40:41], v[160:161] op_sel_hi:[1,0]
	v_lshl_add_u64 v[162:163], v[162:163], 0, v[142:143]
	v_exp_f32_e32 v152, v152
	v_exp_f32_e32 v153, v153
	v_exp_f32_e32 v154, v154
	v_exp_f32_e32 v155, v155
	v_exp_f32_e32 v156, v156
	v_exp_f32_e32 v157, v157
	v_exp_f32_e32 v158, v158
	v_exp_f32_e32 v159, v159
	v_pk_add_f32 v[152:153], v[152:153], 1.0 op_sel_hi:[1,0]
	v_pk_add_f32 v[154:155], v[154:155], 1.0 op_sel_hi:[1,0]
	v_pk_add_f32 v[156:157], v[156:157], 1.0 op_sel_hi:[1,0]
	v_pk_add_f32 v[158:159], v[158:159], 1.0 op_sel_hi:[1,0]
	v_rcp_f32_e32 v152, v152
	v_rcp_f32_e32 v153, v153
	v_rcp_f32_e32 v154, v154
	v_rcp_f32_e32 v155, v155
	v_rcp_f32_e32 v156, v156
	v_rcp_f32_e32 v157, v157
	v_rcp_f32_e32 v158, v158
	v_rcp_f32_e32 v159, v159
	v_pk_mul_f32 v[152:153], v[46:47], v[152:153]
	v_pk_mul_f32 v[154:155], v[48:49], v[154:155]
; __device__ __forceinline__ unsigned cvt_pk_bf16(float lo, float hi) { unsigned r; asm volatile("v_cvt_pk_bf16_f32 %0, %1, %2" : "=v"(r) : "v"(lo), "v"(hi)); return r; }
; __device__ __forceinline__ float silu_f(float g) { return g * __builtin_amdgcn_rcpf(1.0f + __expf(-g)); }
;     __device__ __forceinline__ void operator()(const f32x4 (&acc)[2][2][4][2], const Unit& u, int wr, int wc, int fr, int fq) const {
;     ...
;             for (int m = 0; m < 4; ++m) {
;                 bf16_t* rowp = O + (size_t)(row0 + ai * HALF + m * 16) * DFF + col0;
;                 const f32x4 g0 = acc[ai][0][m][0], g1 = acc[ai][0][m][1], u0 = acc[ai][1][m][0], u1 = acc[ai][1][m][1];
;                 u32x4 w;
;                 w.x = cvt_pk_bf16(silu_f(g0[0]) * u0[0], silu_f(g0[1]) * u0[1]);
;                 w.y = cvt_pk_bf16(silu_f(g0[2]) * u0[2], silu_f(g0[3]) * u0[3]);
;                 w.z = cvt_pk_bf16(silu_f(g1[0]) * u1[0], silu_f(g1[1]) * u1[1]);
;                 w.w = cvt_pk_bf16(silu_f(g1[2]) * u1[2], silu_f(g1[3]) * u1[3]);
;                 *(u32x4*)rowp = w;
;             }
	v_pk_mul_f32 v[156:157], v[38:39], v[156:157]
	v_pk_mul_f32 v[158:159], v[40:41], v[158:159]
	v_pk_mul_f32 v[152:153], v[42:43], v[152:153]
	v_pk_mul_f32 v[154:155], v[44:45], v[154:155]
	v_pk_mul_f32 v[156:157], v[34:35], v[156:157]
	v_pk_mul_f32 v[158:159], v[36:37], v[158:159]
	v_cvt_pk_bf16_f32 v42, v152, v153
	v_cvt_pk_bf16_f32 v43, v154, v155
	v_cvt_pk_bf16_f32 v44, v156, v157
	v_cvt_pk_bf16_f32 v45, v158, v159
	global_store_dwordx4 v[162:163], v[42:45], off
	v_add_u32_e32 v149, 0xa0, v148
	v_mad_i64_i32 v[150:151], s[52:53], v149, s79, v[140:141]
	v_pk_mul_f32 v[152:153], v[30:31], v[160:161] op_sel_hi:[1,0]
	v_pk_mul_f32 v[154:155], v[32:33], v[160:161] op_sel_hi:[1,0]
	v_pk_mul_f32 v[156:157], v[22:23], v[160:161] op_sel_hi:[1,0]
	v_pk_mul_f32 v[158:159], v[24:25], v[160:161] op_sel_hi:[1,0]
	v_lshl_add_u64 v[150:151], v[150:151], 0, v[142:143]
	v_exp_f32_e32 v152, v152
	v_exp_f32_e32 v153, v153
	v_exp_f32_e32 v154, v154
	v_exp_f32_e32 v155, v155
	v_exp_f32_e32 v156, v156
	v_exp_f32_e32 v157, v157
	v_exp_f32_e32 v158, v158
	v_exp_f32_e32 v159, v159
	v_pk_add_f32 v[152:153], v[152:153], 1.0 op_sel_hi:[1,0]
	v_pk_add_f32 v[154:155], v[154:155], 1.0 op_sel_hi:[1,0]
	v_pk_add_f32 v[156:157], v[156:157], 1.0 op_sel_hi:[1,0]
	v_pk_add_f32 v[158:159], v[158:159], 1.0 op_sel_hi:[1,0]
	v_rcp_f32_e32 v152, v152
	v_rcp_f32_e32 v153, v153
	v_rcp_f32_e32 v154, v154
	v_rcp_f32_e32 v155, v155
	v_rcp_f32_e32 v156, v156
	v_rcp_f32_e32 v157, v157
	v_rcp_f32_e32 v158, v158
	v_rcp_f32_e32 v159, v159
	v_pk_mul_f32 v[152:153], v[30:31], v[152:153]
	v_pk_mul_f32 v[154:155], v[32:33], v[154:155]
	v_pk_mul_f32 v[156:157], v[22:23], v[156:157]
	v_pk_mul_f32 v[158:159], v[24:25], v[158:159]
	v_pk_mul_f32 v[152:153], v[26:27], v[152:153]
	v_pk_mul_f32 v[154:155], v[28:29], v[154:155]
	v_pk_mul_f32 v[156:157], v[18:19], v[156:157]
	v_pk_mul_f32 v[158:159], v[20:21], v[158:159]
	v_cvt_pk_bf16_f32 v26, v152, v153
	v_cvt_pk_bf16_f32 v27, v154, v155
	v_cvt_pk_bf16_f32 v28, v156, v157
	v_cvt_pk_bf16_f32 v29, v158, v159
	global_store_dwordx4 v[150:151], v[26:29], off
	v_add_u32_e32 v149, 0xb0, v148
	v_mad_i64_i32 v[162:163], s[52:53], v149, s79, v[140:141]
	v_pk_mul_f32 v[152:153], v[14:15], v[160:161] op_sel_hi:[1,0]
	v_pk_mul_f32 v[154:155], v[16:17], v[160:161] op_sel_hi:[1,0]
	v_pk_mul_f32 v[156:157], v[6:7], v[160:161] op_sel_hi:[1,0]
	v_pk_mul_f32 v[158:159], v[8:9], v[160:161] op_sel_hi:[1,0]
	v_lshl_add_u64 v[162:163], v[162:163], 0, v[142:143]
	v_exp_f32_e32 v152, v152
	v_exp_f32_e32 v153, v153
	v_exp_f32_e32 v154, v154
	v_exp_f32_e32 v155, v155
	v_exp_f32_e32 v156, v156
	v_exp_f32_e32 v157, v157
	v_exp_f32_e32 v158, v158
	v_exp_f32_e32 v159, v159
	v_pk_add_f32 v[152:153], v[152:153], 1.0 op_sel_hi:[1,0]
	v_pk_add_f32 v[154:155], v[154:155], 1.0 op_sel_hi:[1,0]
	v_pk_add_f32 v[156:157], v[156:157], 1.0 op_sel_hi:[1,0]
	v_pk_add_f32 v[158:159], v[158:159], 1.0 op_sel_hi:[1,0]
	v_rcp_f32_e32 v152, v152
	v_rcp_f32_e32 v153, v153
	v_rcp_f32_e32 v154, v154
	v_rcp_f32_e32 v155, v155
	v_rcp_f32_e32 v156, v156
	v_rcp_f32_e32 v157, v157
	v_rcp_f32_e32 v158, v158
	v_rcp_f32_e32 v159, v159
	v_pk_mul_f32 v[152:153], v[14:15], v[152:153]
	v_pk_mul_f32 v[154:155], v[16:17], v[154:155]
	v_pk_mul_f32 v[156:157], v[6:7], v[156:157]
	v_pk_mul_f32 v[158:159], v[8:9], v[158:159]
	v_pk_mul_f32 v[152:153], v[10:11], v[152:153]
	v_pk_mul_f32 v[154:155], v[12:13], v[154:155]
	v_pk_mul_f32 v[156:157], v[2:3], v[156:157]
	v_pk_mul_f32 v[158:159], v[4:5], v[158:159]
	v_cvt_pk_bf16_f32 v10, v152, v153
	v_cvt_pk_bf16_f32 v11, v154, v155
	v_cvt_pk_bf16_f32 v12, v156, v157
	v_cvt_pk_bf16_f32 v13, v158, v159
	global_store_dwordx4 v[162:163], v[10:13], off
	s_mov_b64 s[52:53], -1
	s_cbranch_vccnz .LBB0_522
	s_andn2_b64 vcc, exec, s[22:23]
	s_cbranch_vccnz .LBB0_521
	s_barrier
	s_branch .LBB0_521

; __global__ void __launch_bounds__(512, 2) fwd_mega(Args args) {
;     ...
;                 for (int i = bx * 512 + tid; i < DEPTH * 1536 * 80; i += G * 512) {
;                     const int l = i / (1536 * 80), r2 = i % (1536 * 80), row = r2 / 80, ch = r2 % 80;
;                     const bool z = row < 768 ? (ch >= 48) : (ch < 48);
;                     if (z) *(u32x4*)((bf16*)(ws + WS_WUP + l * SZ_WUP) + (size_t)row * 640 + ch * 8) = (u32x4){0u, 0u, 0u, 0u};
;                 }
.LBB0_1155:
	s_mov_b32 s5, 0x88888889
	s_waitcnt lgkmcnt(0)
	v_mul_hi_i32 v2, v0, s5
	v_add_u32_e32 v2, v2, v0
	v_lshrrev_b32_e32 v3, 31, v2
	v_add_u32_sdwa v2, sext(v2), v3 dst_sel:DWORD dst_unused:UNUSED_PAD src0_sel:WORD_1 src1_sel:DWORD
	v_mul_i32_i24_e32 v3, 0x1e000, v2
	v_sub_u32_e32 v5, v0, v3
	s_mov_b32 s5, 0x66666667
	v_mul_hi_i32 v3, v5, s5
	v_lshrrev_b32_e32 v4, 31, v3
	v_ashrrev_i32_e32 v3, 5, v3
	v_add_u32_e32 v3, v3, v4
	s_movk_i32 s5, 0x50
	v_mul_lo_u32 v4, v3, s5
	s_mov_b32 s5, 0x1e000
	v_mad_i32_i24 v4, v2, s5, v4
	v_sub_u32_e32 v4, v0, v4
	s_mov_b32 s5, 0xf000
	v_cmp_gt_i32_e32 vcc, s5, v5
	v_cmp_gt_i32_e64 s[40:41], 48, v4
	s_xor_b64 s[6:7], vcc, s[40:41]
	s_and_saveexec_b64 s[26:27], s[6:7]
	s_cbranch_execz .LBB0_1154
	s_movk_i32 s5, 0x280
	v_mul_hi_i32_i24_e32 v7, 0x1e0000, v2
	v_mul_i32_i24_e32 v6, 0x1e0000, v2
	v_mul_lo_u32 v2, v3, s5
	v_lshl_add_u64 v[6:7], s[20:21], 0, v[6:7]
	v_ashrrev_i32_e32 v3, 31, v2
	v_lshlrev_b32_e32 v4, 3, v4
	v_lshl_add_u64 v[2:3], v[2:3], 1, v[6:7]
	v_ashrrev_i32_e32 v5, 31, v4
	v_lshl_add_u64 v[2:3], v[4:5], 1, v[2:3]
	global_store_dwordx4 v[2:3], v[250:253], off
	s_branch .LBB0_1154

; __global__ void __launch_bounds__(512, 2) fwd_mega(Args args) {
;     ...
;                     for (int o = tid; o < 9 * 256; o += 512) {
;                         const int r = o >> 8, cc = o & 255; float sm = ap->in[5][l * (NMOD * DM) + n0 + cc];
; #pragma unroll
;                         for (int k2 = 0; k2 < 8; ++k2) sm += red[(k2 * 9 + r) * 256 + cc];
;                         MOD[(size_t)(l * 9 + r) * (NMOD * DM) + n0 + cc] = sm;
;                     }
.LBB0_1171:
	v_or_b32_sdwa v6, v4, s4 dst_sel:DWORD dst_unused:UNUSED_PAD src0_sel:BYTE_0 src1_sel:DWORD
	v_ashrrev_i32_e32 v7, 31, v6
	s_waitcnt vmcnt(0) lgkmcnt(0)
	v_lshl_add_u64 v[6:7], v[6:7], 2, v[2:3]
	flat_load_dword v5, v[6:7]
	v_ashrrev_i32_e32 v8, 8, v4
	v_lshlrev_b32_sdwa v0, v229, v4 dst_sel:DWORD dst_unused:UNUSED_PAD src0_sel:DWORD src1_sel:BYTE_0
	v_lshlrev_b32_e32 v10, 10, v8
	v_mov_b64_e32 v[6:7], s[20:21]
	v_add_u32_e32 v9, 0x200, v4
	s_movk_i32 s5, 0x6ff
	v_add_u32_e32 v8, s24, v8
	v_add3_u32 v10, 0, v0, v10
	v_cmp_lt_i32_e64 s[40:41], s5, v4
	v_mov_b32_e32 v4, v9
	v_mad_i64_i32 v[6:7], s[6:7], v8, s16, v[6:7]
	v_add_u32_e32 v14, 0x9000, v10
	ds_read2st64_b32 v[8:9], v10 offset0:144 offset1:180
	ds_read2st64_b32 v[10:11], v10 offset0:216 offset1:252
	v_lshl_add_u64 v[6:7], v[6:7], 0, v[0:1]
	ds_read2st64_b32 v[12:13], v14 offset0:144 offset1:180
	ds_read2st64_b32 v[14:15], v14 offset0:216 offset1:252
	s_or_b64 s[14:15], s[40:41], s[14:15]
	s_waitcnt vmcnt(0) lgkmcnt(0)
	v_add_f32_e32 v0, v5, v8
	v_add_f32_e32 v0, v0, v9
	v_add_f32_e32 v0, v0, v10
	v_add_f32_e32 v0, v0, v11
	v_add_f32_e32 v0, v0, v12
	v_add_f32_e32 v0, v0, v13
	v_add_f32_e32 v0, v0, v14
	v_add_f32_e32 v0, v0, v15
	global_store_dword v[6:7], v0, off
	s_andn2_b64 exec, exec, s[14:15]
	s_cbranch_execnz .LBB0_1171
	s_branch .LBB0_1166
